# s5y items: waves 4-7 take the mirrored position quarter (tq' = 3 - tq) so each SIMD hosts one long and one short intra-chunk wave
# speedup vs baseline: 1.0535x; 1.0035x over previous
; #define LAS __attribute__((address_space(3)))
; __device__ __forceinline__ unsigned xb_xcc_id() { return (unsigned)__builtin_amdgcn_s_getreg((3 << 11) | 20) & 0xFu; }
; #define REP(k) for (int rep_ = 0; rep_ < (((DUPMASK) >> (k)) & 1 ? 2 : 1); ++rep_)
; #define PHASE_IDS() const int wave = wave_s; int tid = lane_id_asm() + 64 * wave_s; asm volatile("" : "+v"(tid)); const int lane = tid & 63; (void)lane; (void)wave
; __device__ __forceinline__ void s5y_item(ArgsRef A, int item, LAS unsigned char* lds, int tid, int lane, int wave) {
;     ...
;     const int ntl = wave >> 2, tq = wave & 3, ntile = 2 * ntp + ntl, n = lane & 15, kq = lane >> 4, chunk = 16 * (ntile & 3) + n, nks = 8 * tq + 8;
;     const size_t row0 = (size_t)b * 4096 + (size_t)chunk * 64;
; __global__ void __launch_bounds__(512, 2) fwd_kernel(Args A0) {
;     ...
;     REP(4) { { PHASE_IDS(); unsigned* ctr = (unsigned*)(ws + WS_CTL) + 512 * rep_; LAS int* qw = (LAS int*)(lds + LDS_QW); const int xcc = (int)(xb_xcc_id() & 7u);
.LBB0_510:
	v_writelane_b32 v255, s94, 9
	v_writelane_b32 v255, s95, 10
	s_or_b64 exec, exec, s[26:27]
	s_lshr_b32 s25, s82, 8
	s_mul_i32 s23, s25, 3
	s_xor_b32 s23, s0, s23
	s_lshl_b32 s36, s23, 4
	s_lshl_b32 s23, s23, 3
	s_cmpk_lt_u32 s82, 0x80
	s_cselect_b64 s[40:41], -1, 0
	s_mul_i32 s5, s90, 0x1100
	s_add_i32 s33, 0, 0x10000
	s_add_i32 s5, s33, s5
	v_writelane_b32 v255, s5, 11
	s_mul_i32 s0, s25, 0x1100
	v_writelane_b32 v255, s25, 12
	s_add_i32 s0, s33, s0
	v_writelane_b32 v255, s0, 13
	s_add_i32 s0, s90, 0xfffffdc0
	v_writelane_b32 v255, s0, 15
	s_mul_i32 s0, s90, 0x2400
	s_add_i32 s85, s0, 0
	s_lshl_b32 s0, s90, 9
	s_add_i32 s0, s0, 0
	s_or_b32 s37, s36, 1
	s_or_b32 s69, s36, 2
	s_or_b32 s26, s36, 3
	s_or_b32 s27, s36, 4
	s_or_b32 s28, s36, 5
	s_or_b32 s29, s36, 6
	s_or_b32 s76, s36, 7
	s_or_b32 s77, s36, 8
	s_or_b32 s24, s36, 9
	s_or_b32 s30, s36, 10
	s_or_b32 s31, s36, 11
	s_or_b32 s80, s36, 12
	s_or_b32 s81, s36, 13
	s_or_b32 s68, s36, 14
	s_or_b32 s72, s36, 15
	s_add_i32 s0, s0, 0x12000
	s_cmp_gt_u32 s82, 63
	v_writelane_b32 v255, s0, 16
	s_cselect_b64 s[34:35], -1, 0
	v_writelane_b32 v255, s34, 17
	s_cmp_lt_u32 s82, 64
	v_mov_b32_e32 v1, 0
	v_writelane_b32 v255, s35, 18
	s_cselect_b64 s[34:35], -1, 0
	v_writelane_b32 v255, s34, 19
	v_mov_b32_e32 v204, 0x358637bd
	v_mov_b32_e32 v205, 0xa00
	v_writelane_b32 v255, s35, 20
	s_and_b64 s[34:35], s[34:35], exec
	s_cselect_b32 s73, 33, 0
	s_lshl_b32 s0, s90, 5
	v_writelane_b32 v255, s0, 6
	s_lshl_b32 s0, s4, 2
	s_add_u32 s94, s96, s0
	s_addc_u32 s95, s97, 0
	s_lshl_b32 s0, s91, 7
	v_writelane_b32 v255, s0, 21
	s_add_i32 s0, s1, 1
	s_and_b32 s0, s0, 7
	s_mov_b32 s89, s0
	s_lshl_b32 s0, s0, 8
	s_add_u32 s4, s96, s0
	s_addc_u32 s5, s97, 0
	v_writelane_b32 v255, s4, 23
	s_add_i32 s0, s1, 2
	s_and_b32 s0, s0, 7
	v_writelane_b32 v255, s5, 24
	v_writelane_b32 v255, s0, 25
	s_lshl_b32 s0, s0, 8
	s_add_u32 s4, s96, s0
	s_addc_u32 s5, s97, 0
	v_writelane_b32 v255, s4, 26
	s_add_i32 s0, s1, 3
	s_and_b32 s0, s0, 7
	v_writelane_b32 v255, s5, 27
	v_writelane_b32 v255, s0, 28
	s_lshl_b32 s0, s0, 8
	s_add_u32 s4, s96, s0
	s_addc_u32 s5, s97, 0
	v_writelane_b32 v255, s4, 29
	s_xor_b32 s0, s91, 4
	s_movk_i32 s34, 0x500
	v_writelane_b32 v255, s5, 30
	v_writelane_b32 v255, s0, 31
	s_lshl_b32 s0, s0, 8
	s_add_u32 s4, s96, s0
	s_addc_u32 s5, s97, 0
	v_writelane_b32 v255, s4, 32
	s_add_i32 s0, s1, 5
	s_and_b32 s0, s0, 7
	v_writelane_b32 v255, s5, 33
	v_writelane_b32 v255, s0, 34
	s_lshl_b32 s0, s0, 8
	s_add_u32 s4, s96, s0
	s_addc_u32 s5, s97, 0
	v_writelane_b32 v255, s4, 35
	s_add_i32 s0, s1, 6
	s_and_b32 s0, s0, 7
	v_writelane_b32 v255, s5, 36
	v_writelane_b32 v255, s0, 37
	s_lshl_b32 s0, s0, 8
	s_add_u32 s4, s96, s0
	s_addc_u32 s5, s97, 0
	v_writelane_b32 v255, s4, 38
	s_add_i32 s1, s1, -1
	s_and_b32 s0, s1, 7
	v_writelane_b32 v255, s5, 39
	v_writelane_b32 v255, s0, 40
	s_lshl_b32 s0, s0, 8
	s_add_u32 s0, s96, s0
	s_addc_u32 s1, s97, 0
	v_writelane_b32 v255, s0, 41
	v_mov_b32_e32 v233, 0xffffe700
	v_mov_b32_e32 v210, 0xffffdd00
	v_writelane_b32 v255, s1, 42
	s_add_i32 s1, 0, 0x22000
	v_writelane_b32 v255, s40, 43
	v_mov_b32_e32 v203, s1
	v_mov_b32_e32 v211, 0xffffd800
	v_writelane_b32 v255, s41, 44
	v_cndmask_b32_e64 v218, 0, 1, s[40:41]
	v_mov_b32_e32 v213, 0xffffd300
	v_mov_b32_e32 v214, 0xffffce00
	v_mov_b32_e32 v215, 0xffffc900
	v_mov_b32_e32 v216, 0xffffc400
	v_mov_b32_e32 v217, 0xffffbf00
	v_mov_b32_e32 v219, 0xffffba00
	v_mbcnt_hi_u32_b32 v232, -1, v212
	v_mov_b32_e32 v16, 0xf149f2ca
	s_mov_b32 s35, 0x10400
	s_mov_b32 s0, 0x2aaaaaab
	s_mov_b32 s49, 0
	s_mov_b64 s[78:79], 0x100
	s_branch .LBB0_514

; #define LAS __attribute__((address_space(3)))
; #define A (*args_opaque((CArgs*)__builtin_amdgcn_kernarg_segment_ptr()))
; __device__ __forceinline__ void s5y_item(ArgsRef A, int item, LAS unsigned char* lds, int tid, int lane, int wave) {
;     ...
;     const bf16_t* fq_ = FT + ((size_t)((g * 64 + 16 * tq) * 4) * 64 + lane) * 8;
;     bf16x8 fa[2][16];
; #pragma unroll
;     for (int tt = 0; tt < 16; ++tt) fa[0][tt] = *(const bf16x8*)(fq_ + (size_t)(tt * 4 + 0) * 512);
;     __syncthreads();
;     const f32x4 dv = *(const f32x4*)(A.in[22] + g * 16 + 4 * kq); u32x2 uw[16];
; #pragma unroll
;     for (int ks = 0; ks < 4; ++ks) {
;         if (ks < 3) {
; #pragma unroll
;             for (int tt = 0; tt < 16; ++tt) fa[(ks + 1) & 1][tt] = *(const bf16x8*)(fq_ + (size_t)(tt * 4 + ks + 1) * 512); }
;         else {
; #pragma unroll
;             for (int tt = 0; tt < 16; ++tt) uw[tt] = *(const u32x2*)(H1 + (row0 + 16 * tq + tt) * NIN + 640 + g * 16 + 4 * kq); }
;         const bf16x8 bs = *(const LAS bf16x8*)(lds + 65536 + ntl * 4352 + n * 272 + (32 * ks + 8 * kq) * 2);
; #pragma unroll
;         for (int tt = 0; tt < 16; ++tt) acc[tt] = __builtin_amdgcn_mfma_f32_16x16x32_bf16(fa[ks & 1][tt], bs, acc[tt], 0, 0, 0);
;     }
.LBB0_841:
	s_lshl_b32 s4, s54, 8
	s_lshl_b32 s5, s36, 2
	s_or_b32 s4, s4, s5
	s_mov_b32 s5, s49
	s_lshl_b64 s[4:5], s[4:5], 10
	s_add_u32 s4, s44, s4
	s_addc_u32 s5, s45, s5
	v_lshlrev_b32_e32 v0, 4, v220
	s_waitcnt vmcnt(7)
	v_lshl_add_u64 v[104:105], s[4:5], 0, v[0:1]
	s_mov_b32 s4, 0x1c01000
	s_waitcnt lgkmcnt(4)
	v_add_co_u32_e32 v28, vcc, s4, v104
	s_mov_b32 s4, 0x1c03000
	s_nop 0
	v_addc_co_u32_e32 v29, vcc, 0, v105, vcc
	v_add_co_u32_e32 v100, vcc, s4, v104
	global_load_dwordx4 v[2:5], v[28:29], off offset:-4096
	s_waitcnt lgkmcnt(0)
	global_load_dwordx4 v[6:9], v[28:29], off
	v_addc_co_u32_e32 v101, vcc, 0, v105, vcc
	global_load_dwordx4 v[10:13], v[100:101], off offset:-4096
	global_load_dwordx4 v[18:21], v[100:101], off
	s_mov_b32 s4, 0x1c05000
	v_add_co_u32_e32 v22, vcc, s4, v104
	s_mov_b32 s4, 0x1c07000
	s_nop 0
	v_addc_co_u32_e32 v23, vcc, 0, v105, vcc
	v_add_co_u32_e32 v102, vcc, s4, v104
	s_mov_b32 s4, 0x1c09000
	s_nop 0
	v_addc_co_u32_e32 v103, vcc, 0, v105, vcc
	v_add_co_u32_e32 v30, vcc, s4, v104
	s_mov_b32 s4, 0x1c0b000
	s_nop 0
	v_addc_co_u32_e32 v31, vcc, 0, v105, vcc
	v_add_co_u32_e32 v98, vcc, s4, v104
	s_mov_b32 s4, 0x1c0d000
	s_nop 0
	v_addc_co_u32_e32 v99, vcc, 0, v105, vcc
	s_waitcnt vmcnt(10)
	v_add_co_u32_e32 v106, vcc, s4, v104
	v_mul_u32_u24_e32 v0, 0x110, v222
	v_and_b32_e32 v14, 48, v198
	v_readlane_b32 s4, v255, 13
	v_addc_co_u32_e32 v107, vcc, 0, v105, vcc
	s_nop 0
	v_add3_u32 v0, s4, v0, v14
	s_mov_b32 s4, 0x1c0f000
	v_add_co_u32_e32 v14, vcc, s4, v104
	global_load_dwordx4 v[24:27], v[22:23], off offset:-4096
	global_load_dwordx4 v[108:111], v[22:23], off
	global_load_dwordx4 v[112:115], v[102:103], off offset:-4096
	global_load_dwordx4 v[116:119], v[102:103], off
	global_load_dwordx4 v[120:123], v[30:31], off offset:-4096
	global_load_dwordx4 v[124:127], v[30:31], off
	global_load_dwordx4 v[128:131], v[98:99], off offset:-4096
	global_load_dwordx4 v[132:135], v[98:99], off
	global_load_dwordx4 v[136:139], v[106:107], off offset:-4096
	v_addc_co_u32_e32 v15, vcc, 0, v105, vcc
	global_load_dwordx4 v[140:143], v[106:107], off
	global_load_dwordx4 v[144:147], v[14:15], off offset:-4096
	global_load_dwordx4 v[148:151], v[14:15], off
	s_barrier
	ds_read_b128 v[152:155], v0
	ds_read_b128 v[156:159], v0 offset:64
	s_mov_b64 s[4:5], 0x1c00000
	v_lshl_add_u64 v[32:33], v[104:105], 0, s[4:5]
	s_mov_b32 s4, 0x1c02000
	s_lshl_b64 s[40:41], s[48:49], 2
	s_waitcnt vmcnt(15) lgkmcnt(1)
	v_mfma_f32_16x16x32_bf16 v[2:5], v[2:5], v[152:155], v[94:97]
	s_waitcnt vmcnt(13)
	v_mfma_f32_16x16x32_bf16 v[10:13], v[10:13], v[152:155], v[86:89]
	s_nop 2
	global_load_dwordx4 v[86:89], v[28:29], off offset:1024
	s_waitcnt vmcnt(13)
	v_mfma_f32_16x16x32_bf16 v[18:21], v[18:21], v[152:155], v[82:85]
	s_nop 2
	global_load_dwordx4 v[82:85], v[32:33], off offset:1024
	s_waitcnt vmcnt(13)
	v_mfma_f32_16x16x32_bf16 v[24:27], v[24:27], v[152:155], v[78:81]
	s_waitcnt vmcnt(6)
	v_mfma_f32_16x16x32_bf16 v[78:81], v[132:135], v[152:155], v[50:53]
	s_nop 2
	v_add_co_u32_e32 v50, vcc, s4, v104
	v_mfma_f32_16x16x32_bf16 v[6:9], v[6:9], v[152:155], v[90:93]
	s_nop 0
	v_addc_co_u32_e32 v51, vcc, 0, v105, vcc
	s_nop 0
	global_load_dwordx4 v[90:93], v[50:51], off offset:1024
	global_load_dwordx4 v[94:97], v[100:101], off offset:1024
	s_mov_b32 s4, 0x1c04000
	v_add_co_u32_e32 v52, vcc, s4, v104
	v_mfma_f32_16x16x32_bf16 v[74:77], v[108:111], v[152:155], v[74:77]
	s_nop 0
	v_addc_co_u32_e32 v53, vcc, 0, v105, vcc
	global_load_dwordx4 v[108:111], v[32:33], off offset:2048
	v_mfma_f32_16x16x32_bf16 v[70:73], v[112:115], v[152:155], v[70:73]
	s_mov_b32 s4, 0x1c06000
	v_add_co_u32_e32 v168, vcc, s4, v104
	v_mfma_f32_16x16x32_bf16 v[66:69], v[116:119], v[152:155], v[66:69]
	global_load_dwordx4 v[112:115], v[52:53], off offset:1024
	global_load_dwordx4 v[116:119], v[28:29], off offset:2048
	v_addc_co_u32_e32 v169, vcc, 0, v105, vcc
	v_mfma_f32_16x16x32_bf16 v[62:65], v[120:123], v[152:155], v[62:65]
	s_mov_b32 s4, 0x1c08000
	v_mfma_f32_16x16x32_bf16 v[58:61], v[124:127], v[152:155], v[58:61]
	v_mfma_f32_16x16x32_bf16 v[54:57], v[128:131], v[152:155], v[54:57]
	s_waitcnt vmcnt(6) lgkmcnt(0)
	v_mfma_f32_16x16x32_bf16 v[86:89], v[86:89], v[156:159], v[6:9]
	global_load_dwordx4 v[120:123], v[22:23], off offset:1024
	s_nop 1
	global_load_dwordx4 v[6:9], v[32:33], off offset:3072
	v_add_co_u32_e32 v32, vcc, s4, v104
	s_waitcnt vmcnt(7)
	v_mfma_f32_16x16x32_bf16 v[82:85], v[82:85], v[156:159], v[2:5]
	v_addc_co_u32_e32 v33, vcc, 0, v105, vcc
	s_mov_b32 s4, 0x1c0a000
	s_waitcnt vmcnt(6)
	v_mfma_f32_16x16x32_bf16 v[2:5], v[90:93], v[156:159], v[10:13]
	s_nop 2
	global_load_dwordx4 v[10:13], v[28:29], off offset:3072
	v_add_co_u32_e32 v170, vcc, s4, v104
	s_waitcnt vmcnt(6)
	v_mfma_f32_16x16x32_bf16 v[90:93], v[94:97], v[156:159], v[18:21]
	global_load_dwordx4 v[94:97], v[168:169], off offset:1024
	global_load_dwordx4 v[124:127], v[102:103], off offset:1024
	global_load_dwordx4 v[128:131], v[52:53], off offset:2048
	global_load_dwordx4 v[132:135], v[22:23], off offset:2048
	v_addc_co_u32_e32 v171, vcc, 0, v105, vcc
	s_waitcnt vmcnt(8)
	v_mfma_f32_16x16x32_bf16 v[112:115], v[112:115], v[156:159], v[24:27]
	s_mov_b32 s4, 0x1c0c000
	v_add_co_u32_e32 v164, vcc, s4, v104
	v_mfma_f32_16x16x32_bf16 v[46:49], v[136:139], v[152:155], v[46:49]
	s_nop 0
	v_addc_co_u32_e32 v165, vcc, 0, v105, vcc
	s_mov_b32 s4, 0x1c0e000
	v_mfma_f32_16x16x32_bf16 v[42:45], v[140:143], v[152:155], v[42:45]
	v_mfma_f32_16x16x32_bf16 v[38:41], v[144:147], v[152:155], v[38:41]
	s_waitcnt vmcnt(6)
; #define LAS __attribute__((address_space(3)))
; __device__ __forceinline__ void s5y_item(ArgsRef A, int item, LAS unsigned char* lds, int tid, int lane, int wave) {
;     ...
; #pragma unroll
;     for (int ks = 0; ks < 4; ++ks) {
;         if (ks < 3) {
; #pragma unroll
;             for (int tt = 0; tt < 16; ++tt) fa[(ks + 1) & 1][tt] = *(const bf16x8*)(fq_ + (size_t)(tt * 4 + ks + 1) * 512); }
;         else {
; #pragma unroll
;             for (int tt = 0; tt < 16; ++tt) uw[tt] = *(const u32x2*)(H1 + (row0 + 16 * tq + tt) * NIN + 640 + g * 16 + 4 * kq); }
;         const bf16x8 bs = *(const LAS bf16x8*)(lds + 65536 + ntl * 4352 + n * 272 + (32 * ks + 8 * kq) * 2);
; #pragma unroll
;         for (int tt = 0; tt < 16; ++tt) acc[tt] = __builtin_amdgcn_mfma_f32_16x16x32_bf16(fa[ks & 1][tt], bs, acc[tt], 0, 0, 0);
;     }
	v_mfma_f32_16x16x32_bf16 v[74:77], v[120:123], v[156:159], v[74:77]
	global_load_dwordx4 v[26:29], v[32:33], off offset:1024
	global_load_dwordx4 v[120:123], v[30:31], off offset:1024
	global_load_dwordx4 v[18:21], v[52:53], off offset:3072
	s_nop 0
	global_load_dwordx4 v[22:25], v[22:23], off offset:3072
	s_waitcnt vmcnt(7)
	v_mfma_f32_16x16x32_bf16 v[70:73], v[94:97], v[156:159], v[70:73]
	s_waitcnt vmcnt(6)
	v_mfma_f32_16x16x32_bf16 v[94:97], v[124:127], v[156:159], v[66:69]
	s_nop 2
	global_load_dwordx4 v[66:69], v[170:171], off offset:1024
	global_load_dwordx4 v[124:127], v[32:33], off offset:2048
	v_mfma_f32_16x16x32_bf16 v[34:37], v[148:151], v[152:155], v[34:37]
	s_waitcnt vmcnt(5)
	v_mfma_f32_16x16x32_bf16 v[136:139], v[26:29], v[156:159], v[62:65]
	s_nop 2
	global_load_dwordx4 v[62:65], v[98:99], off offset:1024
	global_load_dwordx4 v[140:143], v[30:31], off offset:2048
	global_load_dwordx4 v[26:29], v[32:33], off offset:3072
	s_waitcnt vmcnt(7)
	v_mfma_f32_16x16x32_bf16 v[120:123], v[120:123], v[156:159], v[58:61]
	s_waitcnt vmcnt(4)
	v_mfma_f32_16x16x32_bf16 v[52:55], v[66:69], v[156:159], v[54:57]
	s_nop 2
	global_load_dwordx4 v[56:59], v[164:165], off offset:1024
	s_nop 0
	global_load_dwordx4 v[30:33], v[30:31], off offset:3072
	s_waitcnt vmcnt(4)
	v_mfma_f32_16x16x32_bf16 v[78:81], v[62:65], v[156:159], v[78:81]
	global_load_dwordx4 v[60:63], v[106:107], off offset:1024
	global_load_dwordx4 v[144:147], v[164:165], off offset:2048
	global_load_dwordx4 v[152:155], v[106:107], off offset:2048
	s_waitcnt vmcnt(4)
	v_mfma_f32_16x16x32_bf16 v[148:151], v[56:59], v[156:159], v[46:49]
	v_add_co_u32_e32 v56, vcc, s4, v104
	s_nop 1
	v_addc_co_u32_e32 v57, vcc, 0, v105, vcc
	s_waitcnt vmcnt(2)
	v_mfma_f32_16x16x32_bf16 v[160:163], v[60:63], v[156:159], v[42:45]
	s_nop 2
	global_load_dwordx4 v[42:45], v[56:57], off offset:1024
	global_load_dwordx4 v[62:65], v[164:165], off offset:3072
	s_waitcnt vmcnt(1)
	v_mfma_f32_16x16x32_bf16 v[164:167], v[42:45], v[156:159], v[38:41]
	s_nop 2
	global_load_dwordx4 v[38:41], v[14:15], off offset:1024
	global_load_dwordx4 v[66:69], v[106:107], off offset:3072
	ds_read_b128 v[46:49], v0 offset:128
	ds_read_b128 v[58:61], v0 offset:192
	s_waitcnt lgkmcnt(1)
	v_mfma_f32_16x16x32_bf16 v[112:115], v[128:131], v[46:49], v[112:115]
	v_mfma_f32_16x16x32_bf16 v[124:127], v[124:127], v[46:49], v[136:139]
	v_mfma_f32_16x16x32_bf16 v[120:123], v[140:143], v[46:49], v[120:123]
	v_mfma_f32_16x16x32_bf16 v[144:147], v[144:147], v[46:49], v[148:151]
	v_mfma_f32_16x16x32_bf16 v[148:151], v[152:155], v[46:49], v[160:163]
	s_waitcnt vmcnt(1)
	v_mfma_f32_16x16x32_bf16 v[42:45], v[38:41], v[156:159], v[34:37]
	v_mfma_f32_16x16x32_bf16 v[38:41], v[108:111], v[46:49], v[82:85]
	v_mfma_f32_16x16x32_bf16 v[34:37], v[116:119], v[46:49], v[86:89]
	s_nop 1
	global_load_dwordx4 v[82:85], v[50:51], off offset:2048
	global_load_dwordx4 v[86:89], v[50:51], off offset:3072
	v_mfma_f32_16x16x32_bf16 v[116:119], v[132:135], v[46:49], v[74:77]
	s_waitcnt lgkmcnt(0)
	v_mfma_f32_16x16x32_bf16 v[180:183], v[6:9], v[58:61], v[38:41]
	v_mov_b32_e32 v6, 0xffffec00
	v_mov_b32_e32 v7, v1
	v_mov_b32_e32 v9, v1
	v_mfma_f32_16x16x32_bf16 v[184:187], v[10:13], v[58:61], v[34:37]
	v_mov_b32_e32 v10, 0xffffe200
	v_mov_b32_e32 v11, v1
	v_mov_b32_e32 v13, v1
	v_mfma_f32_16x16x32_bf16 v[38:41], v[26:29], v[58:61], v[124:127]
	v_mfma_f32_16x16x32_bf16 v[34:37], v[30:33], v[58:61], v[120:123]
	s_waitcnt vmcnt(1)
	v_mfma_f32_16x16x32_bf16 v[104:107], v[82:85], v[46:49], v[2:5]
	s_nop 2
	global_load_dwordx4 v[2:5], v[100:101], off offset:2048
	global_load_dwordx4 v[108:111], v[100:101], off offset:3072
	s_waitcnt vmcnt(2)
	v_mfma_f32_16x16x32_bf16 v[74:77], v[86:89], v[58:61], v[104:107]
	s_waitcnt vmcnt(1)
	v_mfma_f32_16x16x32_bf16 v[90:93], v[2:5], v[46:49], v[90:93]
	global_load_dwordx4 v[2:5], v[168:169], off offset:2048
	global_load_dwordx4 v[128:131], v[168:169], off offset:3072
	s_waitcnt vmcnt(1)
	v_mfma_f32_16x16x32_bf16 v[132:135], v[2:5], v[46:49], v[70:73]
	global_load_dwordx4 v[2:5], v[102:103], off offset:2048
	s_nop 0
	global_load_dwordx4 v[100:103], v[102:103], off offset:3072
	s_waitcnt vmcnt(1)
	v_mfma_f32_16x16x32_bf16 v[156:159], v[2:5], v[46:49], v[94:97]
	global_load_dwordx4 v[2:5], v[170:171], off offset:2048
	global_load_dwordx4 v[70:73], v[98:99], off offset:2048
	global_load_dwordx4 v[136:139], v[170:171], off offset:3072
	s_waitcnt vmcnt(1)
	v_mfma_f32_16x16x32_bf16 v[172:175], v[70:73], v[46:49], v[78:81]
	v_or_b32_e32 v70, s36, v221
	s_nop 1
	v_lshlrev_b32_e32 v78, 10, v70
	v_mfma_f32_16x16x32_bf16 v[140:143], v[2:5], v[46:49], v[52:55]
	global_load_dwordx4 v[2:5], v[56:57], off offset:2048
	global_load_dwordx4 v[168:171], v[98:99], off offset:3072
	s_load_dwordx2 s[4:5], s[52:53], 0xb0
	global_load_dwordx4 v[50:53], v[14:15], off offset:2048
	v_or_b32_e32 v98, 15, v70
	global_load_dwordx4 v[152:155], v[56:57], off offset:3072
	global_load_dwordx4 v[160:163], v[14:15], off offset:3072
	v_mul_u32_u24_e32 v0, 0x500, v98
	s_waitcnt lgkmcnt(0)
; #define LAS __attribute__((address_space(3)))
; __device__ __forceinline__ unsigned pk2(float lo, float hi) { f32x2_t v = {lo, hi}; bf16x2_t b = __builtin_convertvector(v, bf16x2_t); return __builtin_bit_cast(unsigned, b); }
; __device__ __forceinline__ float bflo(unsigned w) { return __uint_as_float(w << 16); }
; __device__ __forceinline__ float bfhi(unsigned w) { return __uint_as_float(w & 0xffff0000u); }
; __device__ __forceinline__ void s5y_item(ArgsRef A, int item, LAS unsigned char* lds, int tid, int lane, int wave) {
;     ...
;             for (int tt = 0; tt < 16; ++tt) uw[tt] = *(const u32x2*)(H1 + (row0 + 16 * tq + tt) * NIN + 640 + g * 16 + 4 * kq); }
;         const bf16x8 bs = *(const LAS bf16x8*)(lds + 65536 + ntl * 4352 + n * 272 + (32 * ks + 8 * kq) * 2);
; #pragma unroll
;         for (int tt = 0; tt < 16; ++tt) acc[tt] = __builtin_amdgcn_mfma_f32_16x16x32_bf16(fa[ks & 1][tt], bs, acc[tt], 0, 0, 0);
;     }
; #pragma unroll
;     for (int tt = 0; tt < 16; ++tt) { const size_t row = row0 + 16 * tq + tt;
;         const float y0 = acc[tt].x + dv.x * bflo(uw[tt].x), y1 = acc[tt].y + dv.y * bfhi(uw[tt].x), y2 = acc[tt].z + dv.z * bflo(uw[tt].y), y3 = acc[tt].w + dv.w * bfhi(uw[tt].y);
;         u32x2 w; w.x = pk2(gelu_tanh(y0), gelu_tanh(y1)); w.y = pk2(gelu_tanh(y2), gelu_tanh(y3)); *(u32x2*)(G + row * 512 + g * 16 + 4 * kq) = w; }
	s_add_u32 s4, s4, s40
	v_mul_u32_u24_e32 v56, 0x500, v70
	s_addc_u32 s5, s5, s41
	v_lshlrev_b32_e32 v0, 1, v0
	s_lshl_b32 s48, s48, 1
	v_mad_u32_u24 v54, v98, s34, v219
	v_mov_b32_e32 v55, v1
	v_lshlrev_b32_e32 v56, 1, v56
	v_mov_b32_e32 v57, v1
	v_lshl_add_u64 v[14:15], s[46:47], 0, v[0:1]
	v_lshlrev_b32_e32 v0, 3, v17
	v_lshl_add_u64 v[54:55], v[54:55], 1, s[46:47]
	v_lshl_add_u64 v[56:57], s[46:47], 0, v[56:57]
	v_lshl_add_u64 v[54:55], v[54:55], 0, s[48:49]
	v_lshl_add_u64 v[56:57], v[56:57], 0, s[48:49]
	v_lshl_add_u64 v[54:55], v[54:55], 0, v[0:1]
	v_lshl_add_u64 v[56:57], v[56:57], 0, v[0:1]
	v_lshl_add_u64 v[14:15], v[14:15], 0, s[48:49]
	v_mad_u32_u24 v6, v98, s34, v6
	v_mad_u32_u24 v10, v98, s34, v10
	v_lshl_add_u64 v[6:7], v[6:7], 1, s[46:47]
	v_mad_u32_u24 v8, v98, s34, v233
	v_lshl_add_u64 v[10:11], v[10:11], 1, s[46:47]
	v_mad_u32_u24 v12, v98, s34, v210
	v_lshl_add_u64 v[6:7], v[6:7], 0, s[48:49]
	v_lshl_add_u64 v[8:9], v[8:9], 1, s[46:47]
	v_lshl_add_u64 v[10:11], v[10:11], 0, s[48:49]
	v_lshl_add_u64 v[12:13], v[12:13], 1, s[46:47]
	v_lshl_add_u64 v[6:7], v[6:7], 0, v[0:1]
	v_lshl_add_u64 v[8:9], v[8:9], 0, s[48:49]
	v_lshl_add_u64 v[10:11], v[10:11], 0, v[0:1]
	v_lshl_add_u64 v[12:13], v[12:13], 0, s[48:49]
	v_mfma_f32_16x16x32_bf16 v[70:73], v[108:111], v[58:61], v[90:93]
	v_lshl_add_u64 v[8:9], v[8:9], 0, v[0:1]
	v_lshl_add_u64 v[12:13], v[12:13], 0, v[0:1]
	s_mov_b64 s[40:41], 0
	s_waitcnt vmcnt(5)
	v_mfma_f32_16x16x32_bf16 v[30:33], v[136:139], v[58:61], v[140:143]
	s_waitcnt vmcnt(4)
	v_mfma_f32_16x16x32_bf16 v[164:167], v[2:5], v[46:49], v[164:167]
	v_mad_u32_u24 v2, v98, s34, v216
	v_mov_b32_e32 v3, v1
	v_lshl_add_u64 v[2:3], v[2:3], 1, s[46:47]
	v_mad_u32_u24 v4, v98, s34, v217
	v_mov_b32_e32 v5, v1
	v_lshl_add_u64 v[2:3], v[2:3], 0, s[48:49]
	v_lshl_add_u64 v[4:5], v[4:5], 1, s[46:47]
	v_lshl_add_u64 v[2:3], v[2:3], 0, v[0:1]
	v_lshl_add_u64 v[4:5], v[4:5], 0, s[48:49]
	v_lshl_add_u64 v[4:5], v[4:5], 0, v[0:1]
	global_load_dwordx2 v[94:95], v[2:3], off offset:1280
	global_load_dwordx2 v[96:97], v[4:5], off offset:1280
	global_load_dwordx2 v[188:189], v[54:55], off offset:1280
	global_load_dwordx2 v[190:191], v[56:57], off offset:1280
	v_lshlrev_b32_e32 v2, 4, v17
	global_load_dwordx4 v[2:5], v2, s[4:5]
	s_waitcnt vmcnt(7)
	v_mfma_f32_16x16x32_bf16 v[176:179], v[50:53], v[46:49], v[42:45]
	s_add_u32 s4, s44, s48
	s_addc_u32 s5, s45, 0
	s_nop 0
	v_lshl_add_u64 v[42:43], v[14:15], 0, v[0:1]
	v_mov_b32_e32 v14, 0xfffff100
	v_mad_u32_u24 v14, v98, s34, v14
	v_mov_b32_e32 v15, v1
	v_lshl_add_u64 v[14:15], v[14:15], 1, s[46:47]
	v_lshl_add_u64 v[14:15], v[14:15], 0, s[48:49]
	v_lshl_add_u64 v[44:45], v[14:15], 0, v[0:1]
	global_load_dwordx2 v[14:15], v[42:43], off offset:1280
	global_load_dwordx2 v[84:85], v[44:45], off offset:1280
	global_load_dwordx2 v[80:81], v[42:43], off offset:-1280
	global_load_dwordx2 v[82:83], v[42:43], off offset:-3840
	global_load_dwordx2 v[86:87], v[6:7], off offset:1280
	global_load_dwordx2 v[88:89], v[8:9], off offset:1280
	global_load_dwordx2 v[90:91], v[10:11], off offset:1280
	global_load_dwordx2 v[92:93], v[12:13], off offset:1280
	v_mad_u32_u24 v10, v98, s34, v214
	v_mov_b32_e32 v11, v1
	v_lshl_add_u64 v[10:11], v[10:11], 1, s[46:47]
	v_lshl_add_u64 v[10:11], v[10:11], 0, s[48:49]
	v_mfma_f32_16x16x32_bf16 v[42:45], v[100:103], v[58:61], v[156:159]
	v_mad_u32_u24 v6, v98, s34, v211
	v_mov_b32_e32 v7, v1
	v_mad_u32_u24 v8, v98, s34, v213
	v_mov_b32_e32 v9, v1
	v_lshl_add_u64 v[100:101], v[10:11], 0, v[0:1]
	v_mad_u32_u24 v10, v98, s34, v215
	v_mov_b32_e32 v11, v1
	v_lshl_add_u64 v[6:7], v[6:7], 1, s[46:47]
	v_lshl_add_u64 v[8:9], v[8:9], 1, s[46:47]
	v_lshl_add_u64 v[10:11], v[10:11], 1, s[46:47]
	v_lshl_add_u64 v[6:7], v[6:7], 0, s[48:49]
	v_lshl_add_u64 v[8:9], v[8:9], 0, s[48:49]
	v_lshl_add_u64 v[10:11], v[10:11], 0, s[48:49]
	v_mfma_f32_16x16x32_bf16 v[54:57], v[18:21], v[58:61], v[112:115]
	v_lshl_add_u64 v[6:7], v[6:7], 0, v[0:1]
	v_lshl_add_u64 v[8:9], v[8:9], 0, v[0:1]
	s_waitcnt vmcnt(9)
	v_lshlrev_b32_e32 v102, 16, v191
	v_mfma_f32_16x16x32_bf16 v[18:21], v[66:69], v[58:61], v[148:151]
	v_lshl_add_u64 v[68:69], v[10:11], 0, v[0:1]
	v_and_b32_e32 v103, 0xffff0000, v191
	s_waitcnt vmcnt(8)
; __device__ __forceinline__ unsigned pk2(float lo, float hi) { f32x2_t v = {lo, hi}; bf16x2_t b = __builtin_convertvector(v, bf16x2_t); return __builtin_bit_cast(unsigned, b); }
; __device__ __forceinline__ float bflo(unsigned w) { return __uint_as_float(w << 16); }
; __device__ __forceinline__ float bfhi(unsigned w) { return __uint_as_float(w & 0xffff0000u); }
; __device__ __forceinline__ float gelu_tanh(float y) {
;     const float z = 0.7978845608028654f * (y + 0.044715f * y * y * y);
;     const float e = __builtin_amdgcn_exp2f(2.885390081777927f * z);
;     const float t = 1.f - 2.f * __builtin_amdgcn_rcpf(e + 1.f);
;     return 0.5f * y * (1.f + t);
; }
; __device__ __forceinline__ void s5y_item(ArgsRef A, int item, LAS unsigned char* lds, int tid, int lane, int wave) {
;     ...
; #pragma unroll
;     for (int tt = 0; tt < 16; ++tt) { const size_t row = row0 + 16 * tq + tt;
;         const float y0 = acc[tt].x + dv.x * bflo(uw[tt].x), y1 = acc[tt].y + dv.y * bfhi(uw[tt].x), y2 = acc[tt].z + dv.z * bflo(uw[tt].y), y3 = acc[tt].w + dv.w * bfhi(uw[tt].y);
;         u32x2 w; w.x = pk2(gelu_tanh(y0), gelu_tanh(y1)); w.y = pk2(gelu_tanh(y2), gelu_tanh(y3)); *(u32x2*)(G + row * 512 + g * 16 + 4 * kq) = w; }
	v_pk_fma_f32 v[102:103], v[4:5], v[102:103], v[182:183]
	v_mfma_f32_16x16x32_bf16 v[50:53], v[22:25], v[58:61], v[116:119]
	v_mul_f32_e32 v79, 0x3d372713, v103
	v_mul_f32_e32 v79, v103, v79
	v_fma_f32 v79, v103, v79, v103
	v_mfma_f32_16x16x32_bf16 v[46:49], v[128:131], v[58:61], v[132:135]
	v_mul_f32_e32 v79, 0x3f4c422a, v79
	v_mul_f32_e32 v79, 0x4038aa3b, v79
	v_exp_f32_e32 v79, v79
	v_mfma_f32_16x16x32_bf16 v[26:29], v[168:171], v[58:61], v[172:175]
	v_mfma_f32_16x16x32_bf16 v[22:25], v[62:65], v[58:61], v[144:147]
	global_load_dwordx2 v[62:63], v[6:7], off offset:1280
	global_load_dwordx2 v[64:65], v[8:9], off offset:1280
	global_load_dwordx2 v[66:67], v[100:101], off offset:1280
	s_nop 0
	global_load_dwordx2 v[68:69], v[68:69], off offset:1280
	v_mfma_f32_16x16x32_bf16 v[10:13], v[152:155], v[58:61], v[164:167]
	v_mfma_f32_16x16x32_bf16 v[6:9], v[160:163], v[58:61], v[176:179]
	v_lshlrev_b32_e32 v58, 16, v190
	v_and_b32_e32 v59, 0xffff0000, v190
	v_pk_fma_f32 v[60:61], v[2:3], v[58:59], v[180:181]
	s_nop 0
	v_mul_f32_e32 v58, 0x3d372713, v60
	v_mul_f32_e32 v58, v60, v58
	v_mul_f32_e32 v59, 0x3d372713, v61
	v_fma_f32 v58, v60, v58, v60
	v_mul_f32_e32 v59, v61, v59
	v_mul_f32_e32 v58, 0x3f4c422a, v58
	v_fma_f32 v59, v61, v59, v61
	v_mul_f32_e32 v58, 0x4038aa3b, v58
	v_mul_f32_e32 v59, 0x3f4c422a, v59
	v_exp_f32_e32 v58, v58
	v_mul_f32_e32 v59, 0x4038aa3b, v59
	v_exp_f32_e32 v59, v59
	v_pk_mul_f32 v[60:61], v[60:61], 0.5 op_sel_hi:[1,0]
	v_add_f32_e32 v58, 1.0, v58
	v_rcp_f32_e32 v100, v58
	v_add_f32_e32 v58, 1.0, v59
	v_rcp_f32_e32 v101, v58
	v_lshl_add_u64 v[58:59], s[4:5], 0, v[0:1]
	v_mul_f32_e32 v0, 0x3d372713, v102
	v_mul_f32_e32 v0, v102, v0
	v_fma_f32 v0, v102, v0, v102
	v_mul_f32_e32 v0, 0x3f4c422a, v0
	v_mul_f32_e32 v0, 0x4038aa3b, v0
	v_exp_f32_e32 v0, v0
	v_pk_fma_f32 v[100:101], v[100:101], 2.0, 1.0 op_sel_hi:[1,0,0] neg_lo:[1,0,0] neg_hi:[1,0,0]
	v_pk_mul_f32 v[102:103], v[102:103], 0.5 op_sel_hi:[1,0]
	v_pk_add_f32 v[100:101], v[100:101], 1.0 op_sel_hi:[1,0]
	v_add_f32_e32 v0, 1.0, v0
	v_rcp_f32_e32 v104, v0
	v_add_f32_e32 v0, 1.0, v79
	v_rcp_f32_e32 v105, v0
	v_pk_mul_f32 v[60:61], v[60:61], v[100:101]
	s_mov_b64 s[4:5], 0x8000000
	v_cvt_pk_bf16_f32 v60, v60, v61
	v_pk_fma_f32 v[100:101], v[104:105], 2.0, 1.0 op_sel_hi:[1,0,0] neg_lo:[1,0,0] neg_hi:[1,0,0]
	v_lshl_add_u64 v[58:59], v[58:59], 0, s[4:5]
	v_pk_add_f32 v[100:101], v[100:101], 1.0 op_sel_hi:[1,0]
	s_nop 0
	v_pk_mul_f32 v[100:101], v[102:103], v[100:101]
	v_lshlrev_b32_e32 v102, 16, v188
	v_and_b32_e32 v103, 0xffff0000, v188
	v_pk_fma_f32 v[102:103], v[2:3], v[102:103], v[184:185]
	s_nop 0
	v_mul_f32_e32 v0, 0x3d372713, v102
	v_mul_f32_e32 v0, v102, v0
	v_mul_f32_e32 v61, 0x3d372713, v103
	v_fma_f32 v0, v102, v0, v102
	v_mul_f32_e32 v61, v103, v61
	v_mul_f32_e32 v0, 0x3f4c422a, v0
	v_fma_f32 v61, v103, v61, v103
	v_mul_f32_e32 v0, 0x4038aa3b, v0
	v_mul_f32_e32 v61, 0x3f4c422a, v61
	v_exp_f32_e32 v0, v0
	v_mul_f32_e32 v61, 0x4038aa3b, v61
	v_exp_f32_e32 v79, v61
	v_cvt_pk_bf16_f32 v61, v100, v101
	v_add_f32_e32 v0, 1.0, v0
	v_rcp_f32_e32 v100, v0
	v_add_f32_e32 v0, 1.0, v79
	v_rcp_f32_e32 v101, v0
	v_mov_b32_e32 v79, v1
	v_lshl_add_u64 v[104:105], v[58:59], 0, v[78:79]
	global_store_dwordx2 v[104:105], v[60:61], off
	v_pk_fma_f32 v[60:61], v[100:101], 2.0, 1.0 op_sel_hi:[1,0,0] neg_lo:[1,0,0] neg_hi:[1,0,0]
	v_lshlrev_b32_e32 v100, 16, v189
	v_and_b32_e32 v101, 0xffff0000, v189
	v_pk_fma_f32 v[100:101], v[4:5], v[100:101], v[186:187]
	v_pk_mul_f32 v[102:103], v[102:103], 0.5 op_sel_hi:[1,0]
	v_mul_f32_e32 v0, 0x3d372713, v100
	v_mul_f32_e32 v0, v100, v0
	v_mul_f32_e32 v79, 0x3d372713, v101
	v_fma_f32 v0, v100, v0, v100
	v_mul_f32_e32 v79, v101, v79
	v_mul_f32_e32 v0, 0x3f4c422a, v0
	v_fma_f32 v79, v101, v79, v101
	v_mul_f32_e32 v0, 0x4038aa3b, v0
	v_mul_f32_e32 v79, 0x3f4c422a, v79
	v_exp_f32_e32 v0, v0
	v_mul_f32_e32 v79, 0x4038aa3b, v79
	v_exp_f32_e32 v79, v79
	v_pk_add_f32 v[60:61], v[60:61], 1.0 op_sel_hi:[1,0]
	v_add_f32_e32 v0, 1.0, v0
	v_rcp_f32_e32 v104, v0
	v_add_f32_e32 v0, 1.0, v79
	v_rcp_f32_e32 v105, v0
	v_pk_mul_f32 v[60:61], v[102:103], v[60:61]
	v_pk_mul_f32 v[100:101], v[100:101], 0.5 op_sel_hi:[1,0]
	v_cvt_pk_bf16_f32 v60, v60, v61
	v_pk_fma_f32 v[102:103], v[104:105], 2.0, 1.0 op_sel_hi:[1,0,0] neg_lo:[1,0,0] neg_hi:[1,0,0]
	s_nop 0
	v_pk_add_f32 v[102:103], v[102:103], 1.0 op_sel_hi:[1,0]
	s_nop 0
	v_pk_mul_f32 v[100:101], v[100:101], v[102:103]
	v_lshlrev_b32_e32 v102, 16, v96
	v_and_b32_e32 v103, 0xffff0000, v96
	v_pk_fma_f32 v[74:75], v[2:3], v[102:103], v[74:75]
	v_lshlrev_b32_e32 v96, 16, v97
	v_mul_f32_e32 v0, 0x3d372713, v74
	v_mul_f32_e32 v0, v74, v0
	v_mul_f32_e32 v61, 0x3d372713, v75
	v_fma_f32 v0, v74, v0, v74
	v_mul_f32_e32 v61, v75, v61
	v_mul_f32_e32 v0, 0x3f4c422a, v0
	v_fma_f32 v61, v75, v61, v75
	v_mul_f32_e32 v0, 0x4038aa3b, v0
	v_mul_f32_e32 v61, 0x3f4c422a, v61
	v_exp_f32_e32 v0, v0
	v_mul_f32_e32 v61, 0x4038aa3b, v61
	v_exp_f32_e32 v79, v61
	v_cvt_pk_bf16_f32 v61, v100, v101
	v_add_f32_e32 v0, 1.0, v0
	v_rcp_f32_e32 v100, v0
	v_add_f32_e32 v0, 1.0, v79
	v_and_b32_e32 v97, 0xffff0000, v97
	v_rcp_f32_e32 v101, v0
	v_or_b32_e32 v0, 0x400, v78
	v_pk_fma_f32 v[76:77], v[4:5], v[96:97], v[76:77]
	v_lshl_add_u64 v[102:103], v[58:59], 0, v[0:1]
	v_mul_f32_e32 v0, 0x3d372713, v76
	v_mul_f32_e32 v0, v76, v0
	v_mul_f32_e32 v79, 0x3d372713, v77
	v_fma_f32 v0, v76, v0, v76
	v_mul_f32_e32 v79, v77, v79
	v_mul_f32_e32 v0, 0x3f4c422a, v0
	v_fma_f32 v79, v77, v79, v77
	v_mul_f32_e32 v0, 0x4038aa3b, v0
	v_mul_f32_e32 v79, 0x3f4c422a, v79
	v_exp_f32_e32 v0, v0
	v_mul_f32_e32 v79, 0x4038aa3b, v79
	v_exp_f32_e32 v79, v79
; __device__ __forceinline__ unsigned pk2(float lo, float hi) { f32x2_t v = {lo, hi}; bf16x2_t b = __builtin_convertvector(v, bf16x2_t); return __builtin_bit_cast(unsigned, b); }
; __device__ __forceinline__ float bflo(unsigned w) { return __uint_as_float(w << 16); }
; __device__ __forceinline__ float bfhi(unsigned w) { return __uint_as_float(w & 0xffff0000u); }
; __device__ __forceinline__ float gelu_tanh(float y) {
;     const float z = 0.7978845608028654f * (y + 0.044715f * y * y * y);
;     const float e = __builtin_amdgcn_exp2f(2.885390081777927f * z);
;     const float t = 1.f - 2.f * __builtin_amdgcn_rcpf(e + 1.f);
;     return 0.5f * y * (1.f + t);
; }
; __device__ __forceinline__ void s5y_item(ArgsRef A, int item, LAS unsigned char* lds, int tid, int lane, int wave) {
;     ...
; #pragma unroll
;     for (int tt = 0; tt < 16; ++tt) { const size_t row = row0 + 16 * tq + tt;
;         const float y0 = acc[tt].x + dv.x * bflo(uw[tt].x), y1 = acc[tt].y + dv.y * bfhi(uw[tt].x), y2 = acc[tt].z + dv.z * bflo(uw[tt].y), y3 = acc[tt].w + dv.w * bfhi(uw[tt].y);
;         u32x2 w; w.x = pk2(gelu_tanh(y0), gelu_tanh(y1)); w.y = pk2(gelu_tanh(y2), gelu_tanh(y3)); *(u32x2*)(G + row * 512 + g * 16 + 4 * kq) = w; }
	global_store_dwordx2 v[102:103], v[60:61], off
	v_add_f32_e32 v0, 1.0, v0
	v_rcp_f32_e32 v96, v0
	v_add_f32_e32 v0, 1.0, v79
	v_rcp_f32_e32 v97, v0
	v_pk_fma_f32 v[60:61], v[100:101], 2.0, 1.0 op_sel_hi:[1,0,0] neg_lo:[1,0,0] neg_hi:[1,0,0]
	v_pk_mul_f32 v[74:75], v[74:75], 0.5 op_sel_hi:[1,0]
	v_pk_add_f32 v[60:61], v[60:61], 1.0 op_sel_hi:[1,0]
	v_pk_mul_f32 v[76:77], v[76:77], 0.5 op_sel_hi:[1,0]
	v_pk_mul_f32 v[60:61], v[74:75], v[60:61]
	v_pk_fma_f32 v[74:75], v[96:97], 2.0, 1.0 op_sel_hi:[1,0,0] neg_lo:[1,0,0] neg_hi:[1,0,0]
	v_cvt_pk_bf16_f32 v60, v60, v61
	v_pk_add_f32 v[74:75], v[74:75], 1.0 op_sel_hi:[1,0]
	s_nop 0
	v_pk_mul_f32 v[74:75], v[76:77], v[74:75]
	v_lshlrev_b32_e32 v76, 16, v94
	v_and_b32_e32 v77, 0xffff0000, v94
	v_pk_fma_f32 v[70:71], v[2:3], v[76:77], v[70:71]
	s_nop 0
	v_mul_f32_e32 v0, 0x3d372713, v70
	v_mul_f32_e32 v0, v70, v0
	v_mul_f32_e32 v61, 0x3d372713, v71
	v_fma_f32 v0, v70, v0, v70
	v_mul_f32_e32 v61, v71, v61
	v_mul_f32_e32 v0, 0x3f4c422a, v0
	v_fma_f32 v61, v71, v61, v71
	v_mul_f32_e32 v0, 0x4038aa3b, v0
	v_mul_f32_e32 v61, 0x3f4c422a, v61
	v_exp_f32_e32 v0, v0
	v_mul_f32_e32 v61, 0x4038aa3b, v61
	v_exp_f32_e32 v76, v61
	v_cvt_pk_bf16_f32 v61, v74, v75
	v_add_f32_e32 v0, 1.0, v0
	v_rcp_f32_e32 v74, v0
	v_add_f32_e32 v0, 1.0, v76
	v_rcp_f32_e32 v75, v0
	v_or_b32_e32 v0, 0x800, v78
	v_lshl_add_u64 v[76:77], v[58:59], 0, v[0:1]
	global_store_dwordx2 v[76:77], v[60:61], off
	v_pk_fma_f32 v[60:61], v[74:75], 2.0, 1.0 op_sel_hi:[1,0,0] neg_lo:[1,0,0] neg_hi:[1,0,0]
	v_lshlrev_b32_e32 v74, 16, v95
	v_and_b32_e32 v75, 0xffff0000, v95
	v_pk_fma_f32 v[72:73], v[4:5], v[74:75], v[72:73]
	v_pk_mul_f32 v[70:71], v[70:71], 0.5 op_sel_hi:[1,0]
	v_mul_f32_e32 v0, 0x3d372713, v72
	v_mul_f32_e32 v0, v72, v0
	v_mul_f32_e32 v74, 0x3d372713, v73
	v_fma_f32 v0, v72, v0, v72
	v_mul_f32_e32 v74, v73, v74
	v_mul_f32_e32 v0, 0x3f4c422a, v0
	v_fma_f32 v74, v73, v74, v73
	v_mul_f32_e32 v0, 0x4038aa3b, v0
	v_mul_f32_e32 v74, 0x3f4c422a, v74
	v_exp_f32_e32 v0, v0
	v_mul_f32_e32 v74, 0x4038aa3b, v74
	v_exp_f32_e32 v75, v74
	v_pk_add_f32 v[60:61], v[60:61], 1.0 op_sel_hi:[1,0]
	v_add_f32_e32 v0, 1.0, v0
	v_rcp_f32_e32 v74, v0
	v_add_f32_e32 v0, 1.0, v75
	v_rcp_f32_e32 v75, v0
	v_pk_mul_f32 v[60:61], v[70:71], v[60:61]
	v_pk_mul_f32 v[72:73], v[72:73], 0.5 op_sel_hi:[1,0]
	v_cvt_pk_bf16_f32 v60, v60, v61
	v_pk_fma_f32 v[70:71], v[74:75], 2.0, 1.0 op_sel_hi:[1,0,0] neg_lo:[1,0,0] neg_hi:[1,0,0]
	s_nop 0
	v_pk_add_f32 v[70:71], v[70:71], 1.0 op_sel_hi:[1,0]
	s_nop 0
	v_pk_mul_f32 v[70:71], v[72:73], v[70:71]
	s_waitcnt vmcnt(3)
	v_lshlrev_b32_e32 v72, 16, v68
	v_and_b32_e32 v73, 0xffff0000, v68
	v_pk_fma_f32 v[54:55], v[2:3], v[72:73], v[54:55]
	s_nop 0
	v_mul_f32_e32 v0, 0x3d372713, v54
	v_mul_f32_e32 v0, v54, v0
	v_mul_f32_e32 v61, 0x3d372713, v55
	v_fma_f32 v0, v54, v0, v54
	v_mul_f32_e32 v61, v55, v61
	v_mul_f32_e32 v0, 0x3f4c422a, v0
	v_fma_f32 v61, v55, v61, v55
	v_mul_f32_e32 v0, 0x4038aa3b, v0
	v_mul_f32_e32 v61, 0x3f4c422a, v61
	v_exp_f32_e32 v0, v0
	v_mul_f32_e32 v61, 0x4038aa3b, v61
	v_exp_f32_e32 v68, v61
	v_cvt_pk_bf16_f32 v61, v70, v71
	v_add_f32_e32 v0, 1.0, v0
	v_rcp_f32_e32 v70, v0
	v_add_f32_e32 v0, 1.0, v68
	v_lshlrev_b32_e32 v68, 16, v69
	v_and_b32_e32 v69, 0xffff0000, v69
	v_rcp_f32_e32 v71, v0
	v_or_b32_e32 v0, 0xc00, v78
	v_pk_fma_f32 v[56:57], v[4:5], v[68:69], v[56:57]
	v_lshl_add_u64 v[72:73], v[58:59], 0, v[0:1]
	v_mul_f32_e32 v0, 0x3d372713, v56
	v_mul_f32_e32 v0, v56, v0
	v_mul_f32_e32 v68, 0x3d372713, v57
	v_fma_f32 v0, v56, v0, v56
	v_mul_f32_e32 v68, v57, v68
	v_mul_f32_e32 v0, 0x3f4c422a, v0
	v_fma_f32 v68, v57, v68, v57
	v_mul_f32_e32 v0, 0x4038aa3b, v0
	v_mul_f32_e32 v68, 0x3f4c422a, v68
	v_exp_f32_e32 v0, v0
	v_mul_f32_e32 v68, 0x4038aa3b, v68
	v_exp_f32_e32 v69, v68
	global_store_dwordx2 v[72:73], v[60:61], off
	v_add_f32_e32 v0, 1.0, v0
	v_rcp_f32_e32 v68, v0
	v_add_f32_e32 v0, 1.0, v69
	v_rcp_f32_e32 v69, v0
	v_pk_fma_f32 v[60:61], v[70:71], 2.0, 1.0 op_sel_hi:[1,0,0] neg_lo:[1,0,0] neg_hi:[1,0,0]
	v_pk_mul_f32 v[54:55], v[54:55], 0.5 op_sel_hi:[1,0]
	v_pk_add_f32 v[60:61], v[60:61], 1.0 op_sel_hi:[1,0]
	v_pk_mul_f32 v[56:57], v[56:57], 0.5 op_sel_hi:[1,0]
	v_pk_mul_f32 v[54:55], v[54:55], v[60:61]
	v_pk_fma_f32 v[60:61], v[68:69], 2.0, 1.0 op_sel_hi:[1,0,0] neg_lo:[1,0,0] neg_hi:[1,0,0]
	v_cvt_pk_bf16_f32 v54, v54, v55
	v_pk_add_f32 v[60:61], v[60:61], 1.0 op_sel_hi:[1,0]
	s_nop 0
	v_pk_mul_f32 v[56:57], v[56:57], v[60:61]
	v_lshlrev_b32_e32 v60, 16, v66
	v_and_b32_e32 v61, 0xffff0000, v66
	v_pk_fma_f32 v[50:51], v[2:3], v[60:61], v[50:51]
	s_nop 0
	v_mul_f32_e32 v0, 0x3d372713, v50
	v_mul_f32_e32 v0, v50, v0
	v_mul_f32_e32 v55, 0x3d372713, v51
	v_fma_f32 v0, v50, v0, v50
	v_mul_f32_e32 v55, v51, v55
	v_mul_f32_e32 v0, 0x3f4c422a, v0
	v_fma_f32 v55, v51, v55, v51
	v_mul_f32_e32 v0, 0x4038aa3b, v0
	v_mul_f32_e32 v55, 0x3f4c422a, v55
	v_exp_f32_e32 v0, v0
	v_mul_f32_e32 v55, 0x4038aa3b, v55
	v_exp_f32_e32 v60, v55
	v_cvt_pk_bf16_f32 v55, v56, v57
	v_add_f32_e32 v0, 1.0, v0
	v_rcp_f32_e32 v56, v0
	v_add_f32_e32 v0, 1.0, v60
	v_rcp_f32_e32 v57, v0
	v_or_b32_e32 v0, 0x1000, v78
	v_lshl_add_u64 v[60:61], v[58:59], 0, v[0:1]
	global_store_dwordx2 v[60:61], v[54:55], off
	v_pk_fma_f32 v[54:55], v[56:57], 2.0, 1.0 op_sel_hi:[1,0,0] neg_lo:[1,0,0] neg_hi:[1,0,0]
	v_lshlrev_b32_e32 v56, 16, v67
	v_and_b32_e32 v57, 0xffff0000, v67
	v_pk_fma_f32 v[52:53], v[4:5], v[56:57], v[52:53]
	v_pk_mul_f32 v[50:51], v[50:51], 0.5 op_sel_hi:[1,0]
	v_mul_f32_e32 v0, 0x3d372713, v52
	v_mul_f32_e32 v0, v52, v0
	v_mul_f32_e32 v56, 0x3d372713, v53
	v_fma_f32 v0, v52, v0, v52
	v_mul_f32_e32 v56, v53, v56
	v_mul_f32_e32 v0, 0x3f4c422a, v0
; __device__ __forceinline__ unsigned pk2(float lo, float hi) { f32x2_t v = {lo, hi}; bf16x2_t b = __builtin_convertvector(v, bf16x2_t); return __builtin_bit_cast(unsigned, b); }
; __device__ __forceinline__ float bflo(unsigned w) { return __uint_as_float(w << 16); }
; __device__ __forceinline__ float bfhi(unsigned w) { return __uint_as_float(w & 0xffff0000u); }
; __device__ __forceinline__ float gelu_tanh(float y) {
;     const float z = 0.7978845608028654f * (y + 0.044715f * y * y * y);
;     const float e = __builtin_amdgcn_exp2f(2.885390081777927f * z);
;     const float t = 1.f - 2.f * __builtin_amdgcn_rcpf(e + 1.f);
;     return 0.5f * y * (1.f + t);
; }
; __device__ __forceinline__ void s5y_item(ArgsRef A, int item, LAS unsigned char* lds, int tid, int lane, int wave) {
;     ...
; #pragma unroll
;     for (int tt = 0; tt < 16; ++tt) { const size_t row = row0 + 16 * tq + tt;
;         const float y0 = acc[tt].x + dv.x * bflo(uw[tt].x), y1 = acc[tt].y + dv.y * bfhi(uw[tt].x), y2 = acc[tt].z + dv.z * bflo(uw[tt].y), y3 = acc[tt].w + dv.w * bfhi(uw[tt].y);
;         u32x2 w; w.x = pk2(gelu_tanh(y0), gelu_tanh(y1)); w.y = pk2(gelu_tanh(y2), gelu_tanh(y3)); *(u32x2*)(G + row * 512 + g * 16 + 4 * kq) = w; }
	v_fma_f32 v56, v53, v56, v53
	v_mul_f32_e32 v0, 0x4038aa3b, v0
	v_mul_f32_e32 v56, 0x3f4c422a, v56
	v_exp_f32_e32 v0, v0
	v_mul_f32_e32 v56, 0x4038aa3b, v56
	v_exp_f32_e32 v57, v56
	v_pk_add_f32 v[54:55], v[54:55], 1.0 op_sel_hi:[1,0]
	v_add_f32_e32 v0, 1.0, v0
	v_rcp_f32_e32 v56, v0
	v_add_f32_e32 v0, 1.0, v57
	v_rcp_f32_e32 v57, v0
	v_pk_mul_f32 v[50:51], v[50:51], v[54:55]
	v_pk_mul_f32 v[52:53], v[52:53], 0.5 op_sel_hi:[1,0]
	v_cvt_pk_bf16_f32 v50, v50, v51
	v_pk_fma_f32 v[54:55], v[56:57], 2.0, 1.0 op_sel_hi:[1,0,0] neg_lo:[1,0,0] neg_hi:[1,0,0]
	s_nop 0
	v_pk_add_f32 v[54:55], v[54:55], 1.0 op_sel_hi:[1,0]
	s_nop 0
	v_pk_mul_f32 v[52:53], v[52:53], v[54:55]
	v_lshlrev_b32_e32 v54, 16, v64
	v_and_b32_e32 v55, 0xffff0000, v64
	v_pk_fma_f32 v[46:47], v[2:3], v[54:55], v[46:47]
	s_nop 0
	v_mul_f32_e32 v0, 0x3d372713, v46
	v_mul_f32_e32 v0, v46, v0
	v_mul_f32_e32 v51, 0x3d372713, v47
	v_fma_f32 v0, v46, v0, v46
	v_mul_f32_e32 v51, v47, v51
	v_mul_f32_e32 v0, 0x3f4c422a, v0
	v_fma_f32 v51, v47, v51, v47
	v_mul_f32_e32 v0, 0x4038aa3b, v0
	v_mul_f32_e32 v51, 0x3f4c422a, v51
	v_exp_f32_e32 v0, v0
	v_mul_f32_e32 v51, 0x4038aa3b, v51
	v_exp_f32_e32 v54, v51
	v_cvt_pk_bf16_f32 v51, v52, v53
	v_add_f32_e32 v0, 1.0, v0
	v_rcp_f32_e32 v52, v0
	v_add_f32_e32 v0, 1.0, v54
	v_rcp_f32_e32 v53, v0
	v_or_b32_e32 v0, 0x1400, v78
	v_lshl_add_u64 v[54:55], v[58:59], 0, v[0:1]
	global_store_dwordx2 v[54:55], v[50:51], off
	v_pk_fma_f32 v[50:51], v[52:53], 2.0, 1.0 op_sel_hi:[1,0,0] neg_lo:[1,0,0] neg_hi:[1,0,0]
	v_lshlrev_b32_e32 v52, 16, v65
	v_and_b32_e32 v53, 0xffff0000, v65
	v_pk_fma_f32 v[48:49], v[4:5], v[52:53], v[48:49]
	v_pk_mul_f32 v[46:47], v[46:47], 0.5 op_sel_hi:[1,0]
	v_mul_f32_e32 v0, 0x3d372713, v48
	v_mul_f32_e32 v0, v48, v0
	v_mul_f32_e32 v52, 0x3d372713, v49
	v_fma_f32 v0, v48, v0, v48
	v_mul_f32_e32 v52, v49, v52
	v_mul_f32_e32 v0, 0x3f4c422a, v0
	v_fma_f32 v52, v49, v52, v49
	v_mul_f32_e32 v0, 0x4038aa3b, v0
	v_mul_f32_e32 v52, 0x3f4c422a, v52
	v_exp_f32_e32 v0, v0
	v_mul_f32_e32 v52, 0x4038aa3b, v52
	v_exp_f32_e32 v53, v52
	v_pk_add_f32 v[50:51], v[50:51], 1.0 op_sel_hi:[1,0]
	v_add_f32_e32 v0, 1.0, v0
	v_rcp_f32_e32 v52, v0
	v_add_f32_e32 v0, 1.0, v53
	v_rcp_f32_e32 v53, v0
	v_pk_mul_f32 v[46:47], v[46:47], v[50:51]
	v_pk_mul_f32 v[48:49], v[48:49], 0.5 op_sel_hi:[1,0]
	v_cvt_pk_bf16_f32 v46, v46, v47
	v_pk_fma_f32 v[50:51], v[52:53], 2.0, 1.0 op_sel_hi:[1,0,0] neg_lo:[1,0,0] neg_hi:[1,0,0]
	s_nop 0
	v_pk_add_f32 v[50:51], v[50:51], 1.0 op_sel_hi:[1,0]
	s_nop 0
	v_pk_mul_f32 v[48:49], v[48:49], v[50:51]
	v_lshlrev_b32_e32 v50, 16, v62
	v_and_b32_e32 v51, 0xffff0000, v62
	v_pk_fma_f32 v[42:43], v[2:3], v[50:51], v[42:43]
	s_nop 0
	v_mul_f32_e32 v0, 0x3d372713, v42
	v_mul_f32_e32 v0, v42, v0
	v_mul_f32_e32 v47, 0x3d372713, v43
	v_fma_f32 v0, v42, v0, v42
	v_mul_f32_e32 v47, v43, v47
	v_mul_f32_e32 v0, 0x3f4c422a, v0
	v_fma_f32 v47, v43, v47, v43
	v_mul_f32_e32 v0, 0x4038aa3b, v0
	v_mul_f32_e32 v47, 0x3f4c422a, v47
	v_exp_f32_e32 v0, v0
	v_mul_f32_e32 v47, 0x4038aa3b, v47
	v_exp_f32_e32 v50, v47
	v_cvt_pk_bf16_f32 v47, v48, v49
	v_add_f32_e32 v0, 1.0, v0
	v_rcp_f32_e32 v48, v0
	v_add_f32_e32 v0, 1.0, v50
	v_rcp_f32_e32 v49, v0
	v_or_b32_e32 v0, 0x1800, v78
	v_lshl_add_u64 v[50:51], v[58:59], 0, v[0:1]
	global_store_dwordx2 v[50:51], v[46:47], off
	v_pk_fma_f32 v[46:47], v[48:49], 2.0, 1.0 op_sel_hi:[1,0,0] neg_lo:[1,0,0] neg_hi:[1,0,0]
	v_lshlrev_b32_e32 v48, 16, v63
	v_and_b32_e32 v49, 0xffff0000, v63
	v_pk_fma_f32 v[44:45], v[4:5], v[48:49], v[44:45]
	v_pk_mul_f32 v[42:43], v[42:43], 0.5 op_sel_hi:[1,0]
	v_mul_f32_e32 v0, 0x3d372713, v44
	v_mul_f32_e32 v0, v44, v0
	v_mul_f32_e32 v48, 0x3d372713, v45
	v_fma_f32 v0, v44, v0, v44
	v_mul_f32_e32 v48, v45, v48
	v_mul_f32_e32 v0, 0x3f4c422a, v0
	v_fma_f32 v48, v45, v48, v45
	v_mul_f32_e32 v0, 0x4038aa3b, v0
	v_mul_f32_e32 v48, 0x3f4c422a, v48
	v_exp_f32_e32 v0, v0
	v_mul_f32_e32 v48, 0x4038aa3b, v48
	v_exp_f32_e32 v49, v48
	v_pk_add_f32 v[46:47], v[46:47], 1.0 op_sel_hi:[1,0]
	v_add_f32_e32 v0, 1.0, v0
	v_rcp_f32_e32 v48, v0
	v_add_f32_e32 v0, 1.0, v49
	v_rcp_f32_e32 v49, v0
	v_pk_mul_f32 v[42:43], v[42:43], v[46:47]
	v_pk_mul_f32 v[44:45], v[44:45], 0.5 op_sel_hi:[1,0]
	v_cvt_pk_bf16_f32 v42, v42, v43
	v_pk_fma_f32 v[46:47], v[48:49], 2.0, 1.0 op_sel_hi:[1,0,0] neg_lo:[1,0,0] neg_hi:[1,0,0]
	s_nop 0
	v_pk_add_f32 v[46:47], v[46:47], 1.0 op_sel_hi:[1,0]
	s_nop 0
	v_pk_mul_f32 v[44:45], v[44:45], v[46:47]
	v_lshlrev_b32_e32 v46, 16, v92
	v_and_b32_e32 v47, 0xffff0000, v92
	v_pk_fma_f32 v[38:39], v[2:3], v[46:47], v[38:39]
	s_nop 0
	v_mul_f32_e32 v0, 0x3d372713, v38
	v_mul_f32_e32 v0, v38, v0
	v_mul_f32_e32 v43, 0x3d372713, v39
	v_fma_f32 v0, v38, v0, v38
	v_mul_f32_e32 v43, v39, v43
	v_mul_f32_e32 v0, 0x3f4c422a, v0
	v_fma_f32 v43, v39, v43, v39
	v_mul_f32_e32 v0, 0x4038aa3b, v0
	v_mul_f32_e32 v43, 0x3f4c422a, v43
	v_exp_f32_e32 v0, v0
	v_mul_f32_e32 v43, 0x4038aa3b, v43
	v_exp_f32_e32 v46, v43
	v_cvt_pk_bf16_f32 v43, v44, v45
	v_add_f32_e32 v0, 1.0, v0
	v_rcp_f32_e32 v44, v0
	v_add_f32_e32 v0, 1.0, v46
	v_rcp_f32_e32 v45, v0
	v_or_b32_e32 v0, 0x1c00, v78
	v_lshl_add_u64 v[46:47], v[58:59], 0, v[0:1]
	global_store_dwordx2 v[46:47], v[42:43], off
	v_pk_fma_f32 v[42:43], v[44:45], 2.0, 1.0 op_sel_hi:[1,0,0] neg_lo:[1,0,0] neg_hi:[1,0,0]
	v_lshlrev_b32_e32 v44, 16, v93
	v_and_b32_e32 v45, 0xffff0000, v93
	v_pk_fma_f32 v[40:41], v[4:5], v[44:45], v[40:41]
	v_pk_mul_f32 v[38:39], v[38:39], 0.5 op_sel_hi:[1,0]
	v_mul_f32_e32 v0, 0x3d372713, v40
	v_mul_f32_e32 v0, v40, v0
	v_mul_f32_e32 v44, 0x3d372713, v41
	v_fma_f32 v0, v40, v0, v40
	v_mul_f32_e32 v44, v41, v44
	v_mul_f32_e32 v0, 0x3f4c422a, v0
; __device__ __forceinline__ unsigned pk2(float lo, float hi) { f32x2_t v = {lo, hi}; bf16x2_t b = __builtin_convertvector(v, bf16x2_t); return __builtin_bit_cast(unsigned, b); }
; __device__ __forceinline__ float bflo(unsigned w) { return __uint_as_float(w << 16); }
; __device__ __forceinline__ float bfhi(unsigned w) { return __uint_as_float(w & 0xffff0000u); }
; __device__ __forceinline__ float gelu_tanh(float y) {
;     const float z = 0.7978845608028654f * (y + 0.044715f * y * y * y);
;     const float e = __builtin_amdgcn_exp2f(2.885390081777927f * z);
;     const float t = 1.f - 2.f * __builtin_amdgcn_rcpf(e + 1.f);
;     return 0.5f * y * (1.f + t);
; }
; __device__ __forceinline__ void s5y_item(ArgsRef A, int item, LAS unsigned char* lds, int tid, int lane, int wave) {
;     ...
; #pragma unroll
;     for (int tt = 0; tt < 16; ++tt) { const size_t row = row0 + 16 * tq + tt;
;         const float y0 = acc[tt].x + dv.x * bflo(uw[tt].x), y1 = acc[tt].y + dv.y * bfhi(uw[tt].x), y2 = acc[tt].z + dv.z * bflo(uw[tt].y), y3 = acc[tt].w + dv.w * bfhi(uw[tt].y);
;         u32x2 w; w.x = pk2(gelu_tanh(y0), gelu_tanh(y1)); w.y = pk2(gelu_tanh(y2), gelu_tanh(y3)); *(u32x2*)(G + row * 512 + g * 16 + 4 * kq) = w; }
	v_fma_f32 v44, v41, v44, v41
	v_mul_f32_e32 v0, 0x4038aa3b, v0
	v_mul_f32_e32 v44, 0x3f4c422a, v44
	v_exp_f32_e32 v0, v0
	v_mul_f32_e32 v44, 0x4038aa3b, v44
	v_exp_f32_e32 v45, v44
	v_pk_add_f32 v[42:43], v[42:43], 1.0 op_sel_hi:[1,0]
	v_add_f32_e32 v0, 1.0, v0
	v_rcp_f32_e32 v44, v0
	v_add_f32_e32 v0, 1.0, v45
	v_rcp_f32_e32 v45, v0
	v_pk_mul_f32 v[38:39], v[38:39], v[42:43]
	v_pk_mul_f32 v[40:41], v[40:41], 0.5 op_sel_hi:[1,0]
	v_cvt_pk_bf16_f32 v38, v38, v39
	v_pk_fma_f32 v[42:43], v[44:45], 2.0, 1.0 op_sel_hi:[1,0,0] neg_lo:[1,0,0] neg_hi:[1,0,0]
	s_nop 0
	v_pk_add_f32 v[42:43], v[42:43], 1.0 op_sel_hi:[1,0]
	s_nop 0
	v_pk_mul_f32 v[40:41], v[40:41], v[42:43]
	v_lshlrev_b32_e32 v42, 16, v90
	v_and_b32_e32 v43, 0xffff0000, v90
	v_pk_fma_f32 v[34:35], v[2:3], v[42:43], v[34:35]
	s_nop 0
	v_mul_f32_e32 v0, 0x3d372713, v34
	v_mul_f32_e32 v0, v34, v0
	v_mul_f32_e32 v39, 0x3d372713, v35
	v_fma_f32 v0, v34, v0, v34
	v_mul_f32_e32 v39, v35, v39
	v_mul_f32_e32 v0, 0x3f4c422a, v0
	v_fma_f32 v39, v35, v39, v35
	v_mul_f32_e32 v0, 0x4038aa3b, v0
	v_mul_f32_e32 v39, 0x3f4c422a, v39
	v_exp_f32_e32 v0, v0
	v_mul_f32_e32 v39, 0x4038aa3b, v39
	v_exp_f32_e32 v42, v39
	v_cvt_pk_bf16_f32 v39, v40, v41
	v_add_f32_e32 v0, 1.0, v0
	v_rcp_f32_e32 v40, v0
	v_add_f32_e32 v0, 1.0, v42
	v_rcp_f32_e32 v41, v0
	v_or_b32_e32 v0, 0x2000, v78
	v_lshl_add_u64 v[42:43], v[58:59], 0, v[0:1]
	global_store_dwordx2 v[42:43], v[38:39], off
	v_pk_fma_f32 v[38:39], v[40:41], 2.0, 1.0 op_sel_hi:[1,0,0] neg_lo:[1,0,0] neg_hi:[1,0,0]
	v_lshlrev_b32_e32 v40, 16, v91
	v_and_b32_e32 v41, 0xffff0000, v91
	v_pk_fma_f32 v[36:37], v[4:5], v[40:41], v[36:37]
	v_pk_mul_f32 v[34:35], v[34:35], 0.5 op_sel_hi:[1,0]
	v_mul_f32_e32 v0, 0x3d372713, v36
	v_mul_f32_e32 v0, v36, v0
	v_mul_f32_e32 v40, 0x3d372713, v37
	v_fma_f32 v0, v36, v0, v36
	v_mul_f32_e32 v40, v37, v40
	v_mul_f32_e32 v0, 0x3f4c422a, v0
	v_fma_f32 v40, v37, v40, v37
	v_mul_f32_e32 v0, 0x4038aa3b, v0
	v_mul_f32_e32 v40, 0x3f4c422a, v40
	v_exp_f32_e32 v0, v0
	v_mul_f32_e32 v40, 0x4038aa3b, v40
	v_exp_f32_e32 v41, v40
	v_pk_add_f32 v[38:39], v[38:39], 1.0 op_sel_hi:[1,0]
	v_add_f32_e32 v0, 1.0, v0
	v_rcp_f32_e32 v40, v0
	v_add_f32_e32 v0, 1.0, v41
	v_rcp_f32_e32 v41, v0
	v_pk_mul_f32 v[34:35], v[34:35], v[38:39]
	v_pk_mul_f32 v[36:37], v[36:37], 0.5 op_sel_hi:[1,0]
	v_cvt_pk_bf16_f32 v34, v34, v35
	v_pk_fma_f32 v[38:39], v[40:41], 2.0, 1.0 op_sel_hi:[1,0,0] neg_lo:[1,0,0] neg_hi:[1,0,0]
	s_nop 0
	v_pk_add_f32 v[38:39], v[38:39], 1.0 op_sel_hi:[1,0]
	s_nop 0
	v_pk_mul_f32 v[36:37], v[36:37], v[38:39]
	v_lshlrev_b32_e32 v38, 16, v88
	v_and_b32_e32 v39, 0xffff0000, v88
	v_pk_fma_f32 v[30:31], v[2:3], v[38:39], v[30:31]
	s_nop 0
	v_mul_f32_e32 v0, 0x3d372713, v30
	v_mul_f32_e32 v0, v30, v0
	v_mul_f32_e32 v35, 0x3d372713, v31
	v_fma_f32 v0, v30, v0, v30
	v_mul_f32_e32 v35, v31, v35
	v_mul_f32_e32 v0, 0x3f4c422a, v0
	v_fma_f32 v35, v31, v35, v31
	v_mul_f32_e32 v0, 0x4038aa3b, v0
	v_mul_f32_e32 v35, 0x3f4c422a, v35
	v_exp_f32_e32 v0, v0
	v_mul_f32_e32 v35, 0x4038aa3b, v35
	v_exp_f32_e32 v38, v35
	v_cvt_pk_bf16_f32 v35, v36, v37
	v_add_f32_e32 v0, 1.0, v0
	v_rcp_f32_e32 v36, v0
	v_add_f32_e32 v0, 1.0, v38
	v_rcp_f32_e32 v37, v0
	v_or_b32_e32 v0, 0x2400, v78
	v_lshl_add_u64 v[38:39], v[58:59], 0, v[0:1]
	global_store_dwordx2 v[38:39], v[34:35], off
	v_pk_fma_f32 v[34:35], v[36:37], 2.0, 1.0 op_sel_hi:[1,0,0] neg_lo:[1,0,0] neg_hi:[1,0,0]
	v_lshlrev_b32_e32 v36, 16, v89
	v_and_b32_e32 v37, 0xffff0000, v89
	v_pk_fma_f32 v[32:33], v[4:5], v[36:37], v[32:33]
	v_pk_mul_f32 v[30:31], v[30:31], 0.5 op_sel_hi:[1,0]
	v_mul_f32_e32 v0, 0x3d372713, v32
	v_mul_f32_e32 v0, v32, v0
	v_mul_f32_e32 v36, 0x3d372713, v33
	v_fma_f32 v0, v32, v0, v32
	v_mul_f32_e32 v36, v33, v36
	v_mul_f32_e32 v0, 0x3f4c422a, v0
	v_fma_f32 v36, v33, v36, v33
	v_mul_f32_e32 v0, 0x4038aa3b, v0
	v_mul_f32_e32 v36, 0x3f4c422a, v36
	v_exp_f32_e32 v0, v0
	v_mul_f32_e32 v36, 0x4038aa3b, v36
	v_exp_f32_e32 v37, v36
	v_pk_add_f32 v[34:35], v[34:35], 1.0 op_sel_hi:[1,0]
	v_add_f32_e32 v0, 1.0, v0
	v_rcp_f32_e32 v36, v0
	v_add_f32_e32 v0, 1.0, v37
	v_rcp_f32_e32 v37, v0
	v_pk_mul_f32 v[30:31], v[30:31], v[34:35]
	v_pk_mul_f32 v[32:33], v[32:33], 0.5 op_sel_hi:[1,0]
	v_cvt_pk_bf16_f32 v30, v30, v31
	v_pk_fma_f32 v[34:35], v[36:37], 2.0, 1.0 op_sel_hi:[1,0,0] neg_lo:[1,0,0] neg_hi:[1,0,0]
	s_nop 0
	v_pk_add_f32 v[34:35], v[34:35], 1.0 op_sel_hi:[1,0]
	s_nop 0
	v_pk_mul_f32 v[32:33], v[32:33], v[34:35]
	v_lshlrev_b32_e32 v34, 16, v86
	v_and_b32_e32 v35, 0xffff0000, v86
	v_pk_fma_f32 v[26:27], v[2:3], v[34:35], v[26:27]
	s_nop 0
	v_mul_f32_e32 v0, 0x3d372713, v26
	v_mul_f32_e32 v0, v26, v0
	v_mul_f32_e32 v31, 0x3d372713, v27
	v_fma_f32 v0, v26, v0, v26
	v_mul_f32_e32 v31, v27, v31
	v_mul_f32_e32 v0, 0x3f4c422a, v0
	v_fma_f32 v31, v27, v31, v27
	v_mul_f32_e32 v0, 0x4038aa3b, v0
	v_mul_f32_e32 v31, 0x3f4c422a, v31
	v_exp_f32_e32 v0, v0
	v_mul_f32_e32 v31, 0x4038aa3b, v31
	v_exp_f32_e32 v34, v31
	v_cvt_pk_bf16_f32 v31, v32, v33
	v_add_f32_e32 v0, 1.0, v0
	v_rcp_f32_e32 v32, v0
	v_add_f32_e32 v0, 1.0, v34
	v_rcp_f32_e32 v33, v0
	v_or_b32_e32 v0, 0x2800, v78
	v_lshl_add_u64 v[34:35], v[58:59], 0, v[0:1]
	global_store_dwordx2 v[34:35], v[30:31], off
	v_pk_fma_f32 v[30:31], v[32:33], 2.0, 1.0 op_sel_hi:[1,0,0] neg_lo:[1,0,0] neg_hi:[1,0,0]
	v_lshlrev_b32_e32 v32, 16, v87
	v_and_b32_e32 v33, 0xffff0000, v87
	v_pk_fma_f32 v[28:29], v[4:5], v[32:33], v[28:29]
	v_pk_mul_f32 v[26:27], v[26:27], 0.5 op_sel_hi:[1,0]
	v_mul_f32_e32 v0, 0x3d372713, v28
	v_mul_f32_e32 v0, v28, v0
	v_mul_f32_e32 v32, 0x3d372713, v29
	v_fma_f32 v0, v28, v0, v28
	v_mul_f32_e32 v32, v29, v32
	v_mul_f32_e32 v0, 0x3f4c422a, v0
; __device__ __forceinline__ unsigned pk2(float lo, float hi) { f32x2_t v = {lo, hi}; bf16x2_t b = __builtin_convertvector(v, bf16x2_t); return __builtin_bit_cast(unsigned, b); }
; __device__ __forceinline__ float bflo(unsigned w) { return __uint_as_float(w << 16); }
; __device__ __forceinline__ float bfhi(unsigned w) { return __uint_as_float(w & 0xffff0000u); }
; __device__ __forceinline__ float gelu_tanh(float y) {
;     const float z = 0.7978845608028654f * (y + 0.044715f * y * y * y);
;     const float e = __builtin_amdgcn_exp2f(2.885390081777927f * z);
;     const float t = 1.f - 2.f * __builtin_amdgcn_rcpf(e + 1.f);
;     return 0.5f * y * (1.f + t);
; }
; __device__ __forceinline__ void s5y_item(ArgsRef A, int item, LAS unsigned char* lds, int tid, int lane, int wave) {
;     ...
; #pragma unroll
;     for (int tt = 0; tt < 16; ++tt) { const size_t row = row0 + 16 * tq + tt;
;         const float y0 = acc[tt].x + dv.x * bflo(uw[tt].x), y1 = acc[tt].y + dv.y * bfhi(uw[tt].x), y2 = acc[tt].z + dv.z * bflo(uw[tt].y), y3 = acc[tt].w + dv.w * bfhi(uw[tt].y);
;         u32x2 w; w.x = pk2(gelu_tanh(y0), gelu_tanh(y1)); w.y = pk2(gelu_tanh(y2), gelu_tanh(y3)); *(u32x2*)(G + row * 512 + g * 16 + 4 * kq) = w; }
	v_fma_f32 v32, v29, v32, v29
	v_mul_f32_e32 v0, 0x4038aa3b, v0
	v_mul_f32_e32 v32, 0x3f4c422a, v32
	v_exp_f32_e32 v0, v0
	v_mul_f32_e32 v32, 0x4038aa3b, v32
	v_exp_f32_e32 v33, v32
	v_pk_add_f32 v[30:31], v[30:31], 1.0 op_sel_hi:[1,0]
	v_add_f32_e32 v0, 1.0, v0
	v_rcp_f32_e32 v32, v0
	v_add_f32_e32 v0, 1.0, v33
	v_rcp_f32_e32 v33, v0
	v_pk_mul_f32 v[26:27], v[26:27], v[30:31]
	v_pk_mul_f32 v[28:29], v[28:29], 0.5 op_sel_hi:[1,0]
	v_cvt_pk_bf16_f32 v26, v26, v27
	v_pk_fma_f32 v[30:31], v[32:33], 2.0, 1.0 op_sel_hi:[1,0,0] neg_lo:[1,0,0] neg_hi:[1,0,0]
	s_nop 0
	v_pk_add_f32 v[30:31], v[30:31], 1.0 op_sel_hi:[1,0]
	s_nop 0
	v_pk_mul_f32 v[28:29], v[28:29], v[30:31]
	v_lshlrev_b32_e32 v30, 16, v84
	v_and_b32_e32 v31, 0xffff0000, v84
	v_pk_fma_f32 v[22:23], v[2:3], v[30:31], v[22:23]
	s_nop 0
	v_mul_f32_e32 v0, 0x3d372713, v22
	v_mul_f32_e32 v0, v22, v0
	v_mul_f32_e32 v27, 0x3d372713, v23
	v_fma_f32 v0, v22, v0, v22
	v_mul_f32_e32 v27, v23, v27
	v_mul_f32_e32 v0, 0x3f4c422a, v0
	v_fma_f32 v27, v23, v27, v23
	v_mul_f32_e32 v0, 0x4038aa3b, v0
	v_mul_f32_e32 v27, 0x3f4c422a, v27
	v_exp_f32_e32 v0, v0
	v_mul_f32_e32 v27, 0x4038aa3b, v27
	v_exp_f32_e32 v30, v27
	v_cvt_pk_bf16_f32 v27, v28, v29
	v_add_f32_e32 v0, 1.0, v0
	v_rcp_f32_e32 v28, v0
	v_add_f32_e32 v0, 1.0, v30
	v_rcp_f32_e32 v29, v0
	v_or_b32_e32 v0, 0x2c00, v78
	v_lshl_add_u64 v[30:31], v[58:59], 0, v[0:1]
	global_store_dwordx2 v[30:31], v[26:27], off
	v_pk_fma_f32 v[26:27], v[28:29], 2.0, 1.0 op_sel_hi:[1,0,0] neg_lo:[1,0,0] neg_hi:[1,0,0]
	v_lshlrev_b32_e32 v28, 16, v85
	v_and_b32_e32 v29, 0xffff0000, v85
	v_pk_fma_f32 v[24:25], v[4:5], v[28:29], v[24:25]
	v_pk_mul_f32 v[22:23], v[22:23], 0.5 op_sel_hi:[1,0]
	v_mul_f32_e32 v0, 0x3d372713, v24
	v_mul_f32_e32 v0, v24, v0
	v_mul_f32_e32 v28, 0x3d372713, v25
	v_fma_f32 v0, v24, v0, v24
	v_mul_f32_e32 v28, v25, v28
	v_mul_f32_e32 v0, 0x3f4c422a, v0
	v_fma_f32 v28, v25, v28, v25
	v_mul_f32_e32 v0, 0x4038aa3b, v0
	v_mul_f32_e32 v28, 0x3f4c422a, v28
	v_exp_f32_e32 v0, v0
	v_mul_f32_e32 v28, 0x4038aa3b, v28
	v_exp_f32_e32 v29, v28
	v_pk_add_f32 v[26:27], v[26:27], 1.0 op_sel_hi:[1,0]
	v_add_f32_e32 v0, 1.0, v0
	v_rcp_f32_e32 v28, v0
	v_add_f32_e32 v0, 1.0, v29
	v_rcp_f32_e32 v29, v0
	v_pk_mul_f32 v[22:23], v[22:23], v[26:27]
	v_pk_mul_f32 v[24:25], v[24:25], 0.5 op_sel_hi:[1,0]
	v_cvt_pk_bf16_f32 v22, v22, v23
	v_pk_fma_f32 v[26:27], v[28:29], 2.0, 1.0 op_sel_hi:[1,0,0] neg_lo:[1,0,0] neg_hi:[1,0,0]
	s_nop 0
	v_pk_add_f32 v[26:27], v[26:27], 1.0 op_sel_hi:[1,0]
	s_nop 0
	v_pk_mul_f32 v[24:25], v[24:25], v[26:27]
	v_lshlrev_b32_e32 v26, 16, v82
	v_and_b32_e32 v27, 0xffff0000, v82
	v_pk_fma_f32 v[18:19], v[2:3], v[26:27], v[18:19]
	s_nop 0
	v_mul_f32_e32 v0, 0x3d372713, v18
	v_mul_f32_e32 v0, v18, v0
	v_mul_f32_e32 v23, 0x3d372713, v19
	v_fma_f32 v0, v18, v0, v18
	v_mul_f32_e32 v23, v19, v23
	v_mul_f32_e32 v0, 0x3f4c422a, v0
	v_fma_f32 v23, v19, v23, v19
	v_mul_f32_e32 v0, 0x4038aa3b, v0
	v_mul_f32_e32 v23, 0x3f4c422a, v23
	v_exp_f32_e32 v0, v0
	v_mul_f32_e32 v23, 0x4038aa3b, v23
	v_exp_f32_e32 v26, v23
	v_cvt_pk_bf16_f32 v23, v24, v25
	v_add_f32_e32 v0, 1.0, v0
	v_rcp_f32_e32 v24, v0
	v_add_f32_e32 v0, 1.0, v26
	v_rcp_f32_e32 v25, v0
	v_or_b32_e32 v0, 0x3000, v78
	v_lshl_add_u64 v[26:27], v[58:59], 0, v[0:1]
	global_store_dwordx2 v[26:27], v[22:23], off
	v_pk_fma_f32 v[22:23], v[24:25], 2.0, 1.0 op_sel_hi:[1,0,0] neg_lo:[1,0,0] neg_hi:[1,0,0]
	v_lshlrev_b32_e32 v24, 16, v83
	v_and_b32_e32 v25, 0xffff0000, v83
	v_pk_fma_f32 v[20:21], v[4:5], v[24:25], v[20:21]
	v_pk_mul_f32 v[18:19], v[18:19], 0.5 op_sel_hi:[1,0]
	v_mul_f32_e32 v0, 0x3d372713, v20
	v_mul_f32_e32 v0, v20, v0
	v_mul_f32_e32 v24, 0x3d372713, v21
	v_fma_f32 v0, v20, v0, v20
	v_mul_f32_e32 v24, v21, v24
	v_mul_f32_e32 v0, 0x3f4c422a, v0
	v_fma_f32 v24, v21, v24, v21
	v_mul_f32_e32 v0, 0x4038aa3b, v0
	v_mul_f32_e32 v24, 0x3f4c422a, v24
	v_exp_f32_e32 v0, v0
	v_mul_f32_e32 v24, 0x4038aa3b, v24
	v_exp_f32_e32 v25, v24
	v_pk_add_f32 v[22:23], v[22:23], 1.0 op_sel_hi:[1,0]
	v_add_f32_e32 v0, 1.0, v0
	v_rcp_f32_e32 v24, v0
	v_add_f32_e32 v0, 1.0, v25
	v_rcp_f32_e32 v25, v0
	v_pk_mul_f32 v[18:19], v[18:19], v[22:23]
; __device__ __forceinline__ unsigned pk2(float lo, float hi) { f32x2_t v = {lo, hi}; bf16x2_t b = __builtin_convertvector(v, bf16x2_t); return __builtin_bit_cast(unsigned, b); }
; __device__ __forceinline__ float bflo(unsigned w) { return __uint_as_float(w << 16); }
; __device__ __forceinline__ float bfhi(unsigned w) { return __uint_as_float(w & 0xffff0000u); }
; __device__ __forceinline__ float gelu_tanh(float y) {
;     const float z = 0.7978845608028654f * (y + 0.044715f * y * y * y);
;     const float e = __builtin_amdgcn_exp2f(2.885390081777927f * z);
;     const float t = 1.f - 2.f * __builtin_amdgcn_rcpf(e + 1.f);
;     return 0.5f * y * (1.f + t);
; }
; __device__ __forceinline__ void s5y_item(ArgsRef A, int item, LAS unsigned char* lds, int tid, int lane, int wave) {
;     ...
; #pragma unroll
;     for (int tt = 0; tt < 16; ++tt) { const size_t row = row0 + 16 * tq + tt;
;         const float y0 = acc[tt].x + dv.x * bflo(uw[tt].x), y1 = acc[tt].y + dv.y * bfhi(uw[tt].x), y2 = acc[tt].z + dv.z * bflo(uw[tt].y), y3 = acc[tt].w + dv.w * bfhi(uw[tt].y);
;         u32x2 w; w.x = pk2(gelu_tanh(y0), gelu_tanh(y1)); w.y = pk2(gelu_tanh(y2), gelu_tanh(y3)); *(u32x2*)(G + row * 512 + g * 16 + 4 * kq) = w; }
	v_pk_mul_f32 v[20:21], v[20:21], 0.5 op_sel_hi:[1,0]
	v_cvt_pk_bf16_f32 v18, v18, v19
	v_pk_fma_f32 v[22:23], v[24:25], 2.0, 1.0 op_sel_hi:[1,0,0] neg_lo:[1,0,0] neg_hi:[1,0,0]
	s_nop 0
	v_pk_add_f32 v[22:23], v[22:23], 1.0 op_sel_hi:[1,0]
	s_nop 0
	v_pk_mul_f32 v[20:21], v[20:21], v[22:23]
	v_lshlrev_b32_e32 v22, 16, v80
	v_and_b32_e32 v23, 0xffff0000, v80
	v_pk_fma_f32 v[10:11], v[2:3], v[22:23], v[10:11]
	s_nop 0
	v_mul_f32_e32 v0, 0x3d372713, v10
	v_mul_f32_e32 v0, v10, v0
	v_mul_f32_e32 v19, 0x3d372713, v11
	v_fma_f32 v0, v10, v0, v10
	v_mul_f32_e32 v19, v11, v19
	v_mul_f32_e32 v0, 0x3f4c422a, v0
	v_fma_f32 v19, v11, v19, v11
	v_mul_f32_e32 v0, 0x4038aa3b, v0
	v_mul_f32_e32 v19, 0x3f4c422a, v19
	v_exp_f32_e32 v0, v0
	v_mul_f32_e32 v19, 0x4038aa3b, v19
	v_exp_f32_e32 v22, v19
	v_cvt_pk_bf16_f32 v19, v20, v21
	v_add_f32_e32 v0, 1.0, v0
	v_rcp_f32_e32 v20, v0
	v_add_f32_e32 v0, 1.0, v22
	v_rcp_f32_e32 v21, v0
	v_or_b32_e32 v0, 0x3400, v78
	v_lshl_add_u64 v[22:23], v[58:59], 0, v[0:1]
	global_store_dwordx2 v[22:23], v[18:19], off
	v_pk_fma_f32 v[18:19], v[20:21], 2.0, 1.0 op_sel_hi:[1,0,0] neg_lo:[1,0,0] neg_hi:[1,0,0]
	v_lshlrev_b32_e32 v20, 16, v81
	v_and_b32_e32 v21, 0xffff0000, v81
	v_pk_fma_f32 v[12:13], v[4:5], v[20:21], v[12:13]
	v_pk_mul_f32 v[10:11], v[10:11], 0.5 op_sel_hi:[1,0]
	v_mul_f32_e32 v0, 0x3d372713, v12
	v_mul_f32_e32 v0, v12, v0
	v_mul_f32_e32 v20, 0x3d372713, v13
	v_fma_f32 v0, v12, v0, v12
	v_mul_f32_e32 v20, v13, v20
	v_mul_f32_e32 v0, 0x3f4c422a, v0
	v_fma_f32 v20, v13, v20, v13
	v_mul_f32_e32 v0, 0x4038aa3b, v0
	v_mul_f32_e32 v20, 0x3f4c422a, v20
	v_exp_f32_e32 v0, v0
	v_mul_f32_e32 v20, 0x4038aa3b, v20
	v_exp_f32_e32 v21, v20
	v_pk_add_f32 v[18:19], v[18:19], 1.0 op_sel_hi:[1,0]
	v_add_f32_e32 v0, 1.0, v0
	v_rcp_f32_e32 v20, v0
	v_add_f32_e32 v0, 1.0, v21
	v_rcp_f32_e32 v21, v0
	v_pk_mul_f32 v[10:11], v[10:11], v[18:19]
	v_pk_mul_f32 v[12:13], v[12:13], 0.5 op_sel_hi:[1,0]
	v_cvt_pk_bf16_f32 v10, v10, v11
	v_pk_fma_f32 v[18:19], v[20:21], 2.0, 1.0 op_sel_hi:[1,0,0] neg_lo:[1,0,0] neg_hi:[1,0,0]
	s_nop 0
	v_pk_add_f32 v[18:19], v[18:19], 1.0 op_sel_hi:[1,0]
	s_nop 0
	v_pk_mul_f32 v[12:13], v[12:13], v[18:19]
	v_lshlrev_b32_e32 v18, 16, v14
	v_and_b32_e32 v19, 0xffff0000, v14
	v_pk_fma_f32 v[2:3], v[2:3], v[18:19], v[6:7]
	v_cvt_pk_bf16_f32 v11, v12, v13
	v_mul_f32_e32 v0, 0x3d372713, v2
	v_mul_f32_e32 v0, v2, v0
	v_mul_f32_e32 v6, 0x3d372713, v3
	v_fma_f32 v0, v2, v0, v2
	v_mul_f32_e32 v6, v3, v6
	v_mul_f32_e32 v0, 0x3f4c422a, v0
	v_fma_f32 v6, v3, v6, v3
	v_mul_f32_e32 v0, 0x4038aa3b, v0
	v_mul_f32_e32 v6, 0x3f4c422a, v6
	v_exp_f32_e32 v0, v0
	v_mul_f32_e32 v6, 0x4038aa3b, v6
	v_exp_f32_e32 v7, v6
	v_pk_mul_f32 v[2:3], v[2:3], 0.5 op_sel_hi:[1,0]
	v_add_f32_e32 v0, 1.0, v0
	v_rcp_f32_e32 v6, v0
	v_add_f32_e32 v0, 1.0, v7
	v_rcp_f32_e32 v7, v0
	v_or_b32_e32 v0, 0x3800, v78
	v_lshl_add_u64 v[12:13], v[58:59], 0, v[0:1]
	global_store_dwordx2 v[12:13], v[10:11], off
	v_lshlrev_b32_e32 v10, 16, v15
	v_and_b32_e32 v11, 0xffff0000, v15
	v_pk_fma_f32 v[4:5], v[4:5], v[10:11], v[8:9]
	v_pk_fma_f32 v[6:7], v[6:7], 2.0, 1.0 op_sel_hi:[1,0,0] neg_lo:[1,0,0] neg_hi:[1,0,0]
	v_mul_f32_e32 v0, 0x3d372713, v4
	v_mul_f32_e32 v0, v4, v0
	v_mul_f32_e32 v8, 0x3d372713, v5
	v_fma_f32 v0, v4, v0, v4
	v_mul_f32_e32 v8, v5, v8
	v_mul_f32_e32 v0, 0x3f4c422a, v0
	v_fma_f32 v8, v5, v8, v5
	v_mul_f32_e32 v0, 0x4038aa3b, v0
	v_mul_f32_e32 v8, 0x3f4c422a, v8
	v_exp_f32_e32 v0, v0
	v_mul_f32_e32 v8, 0x4038aa3b, v8
	v_exp_f32_e32 v9, v8
	v_pk_add_f32 v[6:7], v[6:7], 1.0 op_sel_hi:[1,0]
	v_add_f32_e32 v0, 1.0, v0
	v_rcp_f32_e32 v8, v0
	v_add_f32_e32 v0, 1.0, v9
	v_rcp_f32_e32 v9, v0
	v_pk_mul_f32 v[2:3], v[2:3], v[6:7]
	v_pk_mul_f32 v[4:5], v[4:5], 0.5 op_sel_hi:[1,0]
	v_lshlrev_b32_e32 v0, 10, v98
	v_pk_fma_f32 v[6:7], v[8:9], 2.0, 1.0 op_sel_hi:[1,0,0] neg_lo:[1,0,0] neg_hi:[1,0,0]
	v_cvt_pk_bf16_f32 v2, v2, v3
	v_pk_add_f32 v[6:7], v[6:7], 1.0 op_sel_hi:[1,0]
	s_nop 0
	v_pk_mul_f32 v[4:5], v[4:5], v[6:7]
	s_nop 0
	v_cvt_pk_bf16_f32 v3, v4, v5
	v_lshl_add_u64 v[4:5], v[58:59], 0, v[0:1]
	global_store_dwordx2 v[4:5], v[2:3], off
